# adaLN-RMSNorm latent loops unrolled x2: rows 2,3 alternate between two register sets so their next-iteration loads are issued at the top of the iteration (full-iteration latency hiding, no store-ack d
# baseline (speedup 1.0000x reference)
; DI unsigned pk2(float lo, float hi) { f32x2 v = {lo, hi}; bf16x2_t b = __builtin_convertvector(v, bf16x2_t); return __builtin_bit_cast(unsigned, b); }
; DI void normmod_phase(const float* xl, const float* xc, const float* g, const float* modl  , int cshift, int cscale, bf16_t* H, int nrows, int gw, int NGW, int lane,
;                       const float* part  , const float* pgate  , float* xc_out) {
;     auto ld = [&](const int row, f32x4 (&v)[4]) __attribute__((always_inline)) -> float {
;         const bool lat = row < ML;
;         const float* xr = lat ? xl + (size_t)row * D : xc + (size_t)(row - ML) * D;
;         float ss = 0.f;
; #pragma unroll
;         for (int j = 0; j < 4; ++j) { v[j] = *(const f32x4*)(xr + lane * 4 + 256 * j);
;             if (part && !lat) {
;                 const size_t po = (size_t)(row - ML) * D + lane * 4 + 256 * j;
;                 const f32x4 p0 = *(const f32x4*)(part + po), p1 = *(const f32x4*)(part + (size_t)MC * D + po), p2 = *(const f32x4*)(part + (size_t)2 * MC * D + po), p3 = *(const f32x4*)(part + (size_t)3 * MC * D + po);
;                 v[j] = v[j] + *(const f32x4*)(pgate + lane * 4 + 256 * j) * ((p0 + p1) + (p2 + p3));
;                 *(f32x4*)(xc_out + po) = v[j]; }
;             ss += (v[j][0] * v[j][0] + v[j][1] * v[j][1]) + (v[j][2] * v[j][2] + v[j][3] * v[j][3]); }
;         return ss; };
;     auto st = [&](const int row, const f32x4 (&v)[4], const float rs) __attribute__((always_inline)) {
;         const float* mp = modl + (size_t)((row < ML) ? (row >> 12) : 16) * 6144;
; #pragma unroll
;         for (int j = 0; j < 4; ++j) { const int c = lane * 4 + 256 * j;
;             const f32x4 gg = *(const f32x4*)(g + c), sh = *(const f32x4*)(mp + cshift * 1024 + c), scl = *(const f32x4*)(mp + cscale * 1024 + c);
;             const f32x4 y = (v[j] * rs) * gg * (scl + 1.f) + sh;
;             u32x2 o; o.x = pk2(y[0], y[1]); o.y = pk2(y[2], y[3]);
;             *(u32x2*)(H + (size_t)row * D + c) = o; } };
;     for (int row = gw * 4; row < (nrows < ML ? nrows : ML); row += NGW * 4) {
;         f32x4 vA[4], vB[4], vC[4], vD[4];
;         float sA = ld(row, vA), sB = ld(row + 1, vB), sC = ld(row + 2, vC), sD = ld(row + 3, vD);
; #pragma unroll
;         for (int o = 1; o < 64; o <<= 1) { sA += __shfl_xor(sA, o); sB += __shfl_xor(sB, o); sC += __shfl_xor(sC, o); sD += __shfl_xor(sD, o); }
.LBB0_317:
	s_add_i32 s30, s20, 0xffff
	s_ashr_i32 s30, s30, 12
	s_mul_hi_i32 s31, s30, 0x6000
	s_mulk_i32 s30, 0x6000
	s_add_u32 s50, s16, s30
	s_addc_u32 s51, s17, s31
	s_add_u32 s50, s50, 0x3000
	s_addc_u32 s51, s51, 0
	s_add_u32 s52, s50, 0x1000
	s_addc_u32 s53, s51, 0
	global_load_dwordx4 v[110:113], v74, s[50:51]
	global_load_dwordx4 v[114:117], v74, s[50:51] offset:1024
	global_load_dwordx4 v[118:121], v74, s[50:51] offset:2048
	global_load_dwordx4 v[122:125], v74, s[50:51] offset:3072
	global_load_dwordx4 v[126:129], v74, s[52:53]
	global_load_dwordx4 v[130:133], v74, s[52:53] offset:1024
	global_load_dwordx4 v[134:137], v74, s[52:53] offset:2048
	global_load_dwordx4 v[138:141], v74, s[52:53] offset:3072
	s_add_i32 s27, s20, s26
	s_add_i32 s27, s27, 0xffff
	s_cmp_gt_i32 s27, 0xffff
	s_cselect_b32 s30, 0, s46
	s_cselect_b32 s31, 0, s47
	s_add_u32 s44, s44, s30
	s_addc_u32 s45, s45, s31
	s_add_u32 s4, s44, 0x1000
	s_addc_u32 s5, s45, 0
	s_add_u32 s34, s44, 0x2000
	s_addc_u32 s35, s45, 0
	s_add_u32 s54, s44, 0x3000
	s_addc_u32 s55, s45, 0
	global_load_dwordx4 v[214:217], v74, s[34:35] nt
	global_load_dwordx4 v[218:221], v74, s[34:35] offset:1024 nt
	global_load_dwordx4 v[222:225], v74, s[34:35] offset:2048 nt
	global_load_dwordx4 v[226:229], v74, s[34:35] offset:3072 nt
	global_load_dwordx4 v[230:233], v74, s[54:55] nt
	global_load_dwordx4 v[234:237], v74, s[54:55] offset:1024 nt
	global_load_dwordx4 v[238:241], v74, s[54:55] offset:2048 nt
	global_load_dwordx4 v[242:245], v74, s[54:55] offset:3072 nt
	s_mov_b32 s30, 0xfffff000
	s_mov_b32 s31, -1
	v_mov_b32_e32 v178, s68
	v_lshl_add_u64 v[198:199], v[76:77], 0, s[30:31]
	s_waitcnt vmcnt(28)
	v_mul_f32_e32 v176, v1, v1
	v_mul_f32_e32 v177, v3, v3
	v_fmac_f32_e32 v176, v0, v0
	v_fmac_f32_e32 v177, v2, v2
	v_add_f32_e32 v172, v176, v177
	v_mul_f32_e32 v176, v5, v5
	v_mul_f32_e32 v177, v7, v7
	v_fmac_f32_e32 v176, v4, v4
	v_fmac_f32_e32 v177, v6, v6
	v_add_f32_e32 v176, v176, v177
	v_add_f32_e32 v172, v172, v176
	v_mul_f32_e32 v176, v9, v9
	v_mul_f32_e32 v177, v11, v11
	v_fmac_f32_e32 v176, v8, v8
	v_fmac_f32_e32 v177, v10, v10
	v_add_f32_e32 v176, v176, v177
	v_add_f32_e32 v172, v172, v176
	v_mul_f32_e32 v176, v13, v13
	v_mul_f32_e32 v177, v15, v15
	v_fmac_f32_e32 v176, v12, v12
	v_fmac_f32_e32 v177, v14, v14
	v_add_f32_e32 v176, v176, v177
	v_add_f32_e32 v172, v172, v176
	s_waitcnt vmcnt(24)
	v_mul_f32_e32 v176, v17, v17
	v_mul_f32_e32 v177, v19, v19
	v_fmac_f32_e32 v176, v16, v16
	v_fmac_f32_e32 v177, v18, v18
	v_add_f32_e32 v173, v176, v177
	v_mul_f32_e32 v176, v21, v21
	v_mul_f32_e32 v177, v23, v23
	v_fmac_f32_e32 v176, v20, v20
	v_fmac_f32_e32 v177, v22, v22
	v_add_f32_e32 v176, v176, v177
	v_add_f32_e32 v173, v173, v176
	v_mul_f32_e32 v176, v25, v25
	v_mul_f32_e32 v177, v27, v27
	v_fmac_f32_e32 v176, v24, v24
	v_fmac_f32_e32 v177, v26, v26
	v_add_f32_e32 v176, v176, v177
	v_add_f32_e32 v173, v173, v176
	v_mul_f32_e32 v176, v29, v29
	v_mul_f32_e32 v177, v31, v31
	v_fmac_f32_e32 v176, v28, v28
	v_fmac_f32_e32 v177, v30, v30
	v_add_f32_e32 v176, v176, v177
	v_add_f32_e32 v173, v173, v176
	s_waitcnt vmcnt(16)
	v_mul_f32_e32 v176, v33, v33
	v_mul_f32_e32 v177, v35, v35
	v_fmac_f32_e32 v176, v32, v32
	v_fmac_f32_e32 v177, v34, v34
	v_add_f32_e32 v174, v176, v177
	v_mul_f32_e32 v176, v37, v37
	v_mul_f32_e32 v177, v39, v39
	v_fmac_f32_e32 v176, v36, v36
	v_fmac_f32_e32 v177, v38, v38
	v_add_f32_e32 v176, v176, v177
	v_add_f32_e32 v174, v174, v176
	v_mul_f32_e32 v176, v41, v41
	v_mul_f32_e32 v177, v43, v43
	v_fmac_f32_e32 v176, v40, v40
	v_fmac_f32_e32 v177, v42, v42
	v_add_f32_e32 v176, v176, v177
	v_add_f32_e32 v174, v174, v176
	v_mul_f32_e32 v176, v45, v45
	v_mul_f32_e32 v177, v47, v47
	v_fmac_f32_e32 v176, v44, v44
	v_fmac_f32_e32 v177, v46, v46
	v_add_f32_e32 v176, v176, v177
	v_add_f32_e32 v174, v174, v176
	v_mul_f32_e32 v176, v49, v49
	v_mul_f32_e32 v177, v51, v51
	v_fmac_f32_e32 v176, v48, v48
	v_fmac_f32_e32 v177, v50, v50
	v_add_f32_e32 v175, v176, v177
	v_mul_f32_e32 v176, v53, v53
	v_mul_f32_e32 v177, v55, v55
	v_fmac_f32_e32 v176, v52, v52
	v_fmac_f32_e32 v177, v54, v54
	v_add_f32_e32 v176, v176, v177
	v_add_f32_e32 v175, v175, v176
	v_mul_f32_e32 v176, v57, v57
	v_mul_f32_e32 v177, v59, v59
	v_fmac_f32_e32 v176, v56, v56
	v_fmac_f32_e32 v177, v58, v58
	v_add_f32_e32 v176, v176, v177
	v_add_f32_e32 v175, v175, v176
	v_mul_f32_e32 v176, v61, v61
	v_mul_f32_e32 v177, v63, v63
	v_fmac_f32_e32 v176, v60, v60
	v_fmac_f32_e32 v177, v62, v62
	v_add_f32_e32 v176, v176, v177
	v_add_f32_e32 v175, v175, v176
	ds_bpermute_b32 v184, v81, v172
	ds_bpermute_b32 v185, v81, v173
	ds_bpermute_b32 v186, v81, v174
	ds_bpermute_b32 v187, v81, v175
	s_waitcnt lgkmcnt(0)
	v_pk_add_f32 v[172:173], v[172:173], v[184:185]
	v_pk_add_f32 v[174:175], v[174:175], v[186:187]
	ds_bpermute_b32 v184, v82, v172
	ds_bpermute_b32 v185, v82, v173
	ds_bpermute_b32 v186, v82, v174
	ds_bpermute_b32 v187, v82, v175
	s_waitcnt lgkmcnt(0)
	v_pk_add_f32 v[172:173], v[172:173], v[184:185]
	v_pk_add_f32 v[174:175], v[174:175], v[186:187]
	ds_bpermute_b32 v184, v83, v172
	ds_bpermute_b32 v185, v83, v173
	ds_bpermute_b32 v186, v83, v174
	ds_bpermute_b32 v187, v83, v175
	s_waitcnt lgkmcnt(0)
	v_pk_add_f32 v[172:173], v[172:173], v[184:185]
	v_pk_add_f32 v[174:175], v[174:175], v[186:187]
	ds_bpermute_b32 v184, v84, v172
	ds_bpermute_b32 v185, v84, v173
	ds_bpermute_b32 v186, v84, v174
	ds_bpermute_b32 v187, v84, v175
	s_waitcnt lgkmcnt(0)
	v_pk_add_f32 v[172:173], v[172:173], v[184:185]
	v_pk_add_f32 v[174:175], v[174:175], v[186:187]
	ds_bpermute_b32 v184, v85, v172
	ds_bpermute_b32 v185, v85, v173
	ds_bpermute_b32 v186, v85, v174
	ds_bpermute_b32 v187, v85, v175
	s_waitcnt lgkmcnt(0)
; DI unsigned pk2(float lo, float hi) { f32x2 v = {lo, hi}; bf16x2_t b = __builtin_convertvector(v, bf16x2_t); return __builtin_bit_cast(unsigned, b); }
; DI void normmod_phase(const float* xl, const float* xc, const float* g, const float* modl  , int cshift, int cscale, bf16_t* H, int nrows, int gw, int NGW, int lane,
;                       const float* part  , const float* pgate  , float* xc_out) {
;     ...
;     auto st = [&](const int row, const f32x4 (&v)[4], const float rs) __attribute__((always_inline)) {
;         const float* mp = modl + (size_t)((row < ML) ? (row >> 12) : 16) * 6144;
; #pragma unroll
;         for (int j = 0; j < 4; ++j) { const int c = lane * 4 + 256 * j;
;             const f32x4 gg = *(const f32x4*)(g + c), sh = *(const f32x4*)(mp + cshift * 1024 + c), scl = *(const f32x4*)(mp + cscale * 1024 + c);
;             const f32x4 y = (v[j] * rs) * gg * (scl + 1.f) + sh;
;             u32x2 o; o.x = pk2(y[0], y[1]); o.y = pk2(y[2], y[3]);
;             *(u32x2*)(H + (size_t)row * D + c) = o; } };
;     for (int row = gw * 4; row < (nrows < ML ? nrows : ML); row += NGW * 4) {
;         f32x4 vA[4], vB[4], vC[4], vD[4];
;         float sA = ld(row, vA), sB = ld(row + 1, vB), sC = ld(row + 2, vC), sD = ld(row + 3, vD);
; #pragma unroll
;         for (int o = 1; o < 64; o <<= 1) { sA += __shfl_xor(sA, o); sB += __shfl_xor(sB, o); sC += __shfl_xor(sC, o); sD += __shfl_xor(sD, o); }
;         st(row, vA, rsqrtf(sA * (1.f / D) + EPS)); st(row + 1, vB, rsqrtf(sB * (1.f / D) + EPS));
;         st(row + 2, vC, rsqrtf(sC * (1.f / D) + EPS)); st(row + 3, vD, rsqrtf(sD * (1.f / D) + EPS));
	v_pk_add_f32 v[172:173], v[172:173], v[184:185]
	v_pk_add_f32 v[174:175], v[174:175], v[186:187]
	ds_bpermute_b32 v184, v86, v172
	ds_bpermute_b32 v185, v86, v173
	ds_bpermute_b32 v186, v86, v174
	ds_bpermute_b32 v187, v86, v175
	s_waitcnt lgkmcnt(0)
	v_pk_add_f32 v[172:173], v[172:173], v[184:185]
	v_pk_add_f32 v[174:175], v[174:175], v[186:187]
	v_fma_f32 v172, v172, s66, v178
	v_fma_f32 v173, v173, s66, v178
	v_fma_f32 v174, v174, s66, v178
	v_fma_f32 v175, v175, s66, v178
	v_mul_f32_e32 v184, 0x4b800000, v172
	v_mul_f32_e32 v185, 0x4b800000, v173
	v_mul_f32_e32 v186, 0x4b800000, v174
	v_mul_f32_e32 v187, 0x4b800000, v175
	s_waitcnt vmcnt(8)
	v_cmp_gt_f32_e64 s[50:51], s62, v172
	v_cmp_gt_f32_e64 s[52:53], s62, v173
	v_cmp_gt_f32_e64 s[30:31], s62, v174
	v_cmp_gt_f32_e32 vcc, s62, v175
	s_nop 1
	v_cndmask_b32_e64 v172, v172, v184, s[50:51]
	v_cndmask_b32_e64 v173, v173, v185, s[52:53]
	v_cndmask_b32_e64 v174, v174, v186, s[30:31]
	v_cndmask_b32_e32 v175, v175, v187, vcc
	v_rsq_f32_e32 v172, v172
	v_rsq_f32_e32 v173, v173
	v_rsq_f32_e32 v174, v174
	v_rsq_f32_e32 v175, v175
	s_nop 0
	v_mul_f32_e32 v184, 0x45800000, v172
	v_mul_f32_e32 v185, 0x45800000, v173
	v_mul_f32_e32 v186, 0x45800000, v174
	v_mul_f32_e32 v187, 0x45800000, v175
	v_cndmask_b32_e64 v188, v172, v184, s[50:51]
	v_cndmask_b32_e64 v190, v173, v185, s[52:53]
	v_cndmask_b32_e64 v192, v174, v186, s[30:31]
	v_cndmask_b32_e32 v194, v175, v187, vcc
	v_pk_add_f32 v[126:127], v[126:127], 1.0 op_sel_hi:[1,0]
	v_pk_add_f32 v[128:129], v[128:129], 1.0 op_sel_hi:[1,0]
	v_pk_add_f32 v[130:131], v[130:131], 1.0 op_sel_hi:[1,0]
	v_pk_add_f32 v[132:133], v[132:133], 1.0 op_sel_hi:[1,0]
	v_pk_add_f32 v[134:135], v[134:135], 1.0 op_sel_hi:[1,0]
	v_pk_add_f32 v[136:137], v[136:137], 1.0 op_sel_hi:[1,0]
	v_pk_add_f32 v[138:139], v[138:139], 1.0 op_sel_hi:[1,0]
	v_pk_add_f32 v[140:141], v[140:141], 1.0 op_sel_hi:[1,0]
	v_pk_mul_f32 v[0:1], v[0:1], v[188:189] op_sel_hi:[1,0]
	v_pk_mul_f32 v[2:3], v[2:3], v[188:189] op_sel_hi:[1,0]
	v_pk_mul_f32 v[0:1], v[156:157], v[0:1]
	v_pk_mul_f32 v[2:3], v[158:159], v[2:3]
	v_pk_fma_f32 v[0:1], v[126:127], v[0:1], v[110:111]
	v_pk_fma_f32 v[2:3], v[128:129], v[2:3], v[112:113]
	v_cvt_pk_bf16_f32 v0, v0, v1
	v_cvt_pk_bf16_f32 v1, v2, v3
	global_store_dwordx2 v[198:199], v[0:1], off offset:-3584
	v_pk_mul_f32 v[4:5], v[4:5], v[188:189] op_sel_hi:[1,0]
	v_pk_mul_f32 v[6:7], v[6:7], v[188:189] op_sel_hi:[1,0]
	v_pk_mul_f32 v[4:5], v[160:161], v[4:5]
	v_pk_mul_f32 v[6:7], v[162:163], v[6:7]
	v_pk_fma_f32 v[4:5], v[130:131], v[4:5], v[114:115]
	v_pk_fma_f32 v[6:7], v[132:133], v[6:7], v[116:117]
	v_cvt_pk_bf16_f32 v4, v4, v5
	v_cvt_pk_bf16_f32 v5, v6, v7
	global_store_dwordx2 v[198:199], v[4:5], off offset:-3072
	v_pk_mul_f32 v[8:9], v[8:9], v[188:189] op_sel_hi:[1,0]
	v_pk_mul_f32 v[10:11], v[10:11], v[188:189] op_sel_hi:[1,0]
	v_pk_mul_f32 v[8:9], v[164:165], v[8:9]
	v_pk_mul_f32 v[10:11], v[166:167], v[10:11]
	v_pk_fma_f32 v[8:9], v[134:135], v[8:9], v[118:119]
	v_pk_fma_f32 v[10:11], v[136:137], v[10:11], v[120:121]
	v_cvt_pk_bf16_f32 v8, v8, v9
	v_cvt_pk_bf16_f32 v9, v10, v11
	global_store_dwordx2 v[198:199], v[8:9], off offset:-2560
	v_pk_mul_f32 v[12:13], v[12:13], v[188:189] op_sel_hi:[1,0]
	v_pk_mul_f32 v[14:15], v[14:15], v[188:189] op_sel_hi:[1,0]
	v_pk_mul_f32 v[12:13], v[168:169], v[12:13]
	v_pk_mul_f32 v[14:15], v[170:171], v[14:15]
	v_pk_fma_f32 v[12:13], v[138:139], v[12:13], v[122:123]
	v_pk_fma_f32 v[14:15], v[140:141], v[14:15], v[124:125]
	v_cvt_pk_bf16_f32 v12, v12, v13
	v_cvt_pk_bf16_f32 v13, v14, v15
	global_store_dwordx2 v[198:199], v[12:13], off offset:-2048
	global_load_dwordx4 v[0:3], v74, s[44:45] nt
	global_load_dwordx4 v[4:7], v74, s[44:45] offset:1024 nt
	global_load_dwordx4 v[8:11], v74, s[44:45] offset:2048 nt
	global_load_dwordx4 v[12:15], v74, s[44:45] offset:3072 nt
	v_pk_mul_f32 v[16:17], v[16:17], v[190:191] op_sel_hi:[1,0]
	v_pk_mul_f32 v[18:19], v[18:19], v[190:191] op_sel_hi:[1,0]
	v_pk_mul_f32 v[16:17], v[156:157], v[16:17]
	v_pk_mul_f32 v[18:19], v[158:159], v[18:19]
	v_pk_fma_f32 v[16:17], v[126:127], v[16:17], v[110:111]
	v_pk_fma_f32 v[18:19], v[128:129], v[18:19], v[112:113]
	v_cvt_pk_bf16_f32 v16, v16, v17
	v_cvt_pk_bf16_f32 v17, v18, v19
	global_store_dwordx2 v[198:199], v[16:17], off offset:-1536
	v_pk_mul_f32 v[20:21], v[20:21], v[190:191] op_sel_hi:[1,0]
	v_pk_mul_f32 v[22:23], v[22:23], v[190:191] op_sel_hi:[1,0]
	v_pk_mul_f32 v[20:21], v[160:161], v[20:21]
	v_pk_mul_f32 v[22:23], v[162:163], v[22:23]
	v_pk_fma_f32 v[20:21], v[130:131], v[20:21], v[114:115]
	v_pk_fma_f32 v[22:23], v[132:133], v[22:23], v[116:117]
	v_cvt_pk_bf16_f32 v20, v20, v21
	v_cvt_pk_bf16_f32 v21, v22, v23
	global_store_dwordx2 v[198:199], v[20:21], off offset:-1024
	v_pk_mul_f32 v[24:25], v[24:25], v[190:191] op_sel_hi:[1,0]
	v_pk_mul_f32 v[26:27], v[26:27], v[190:191] op_sel_hi:[1,0]
	v_pk_mul_f32 v[24:25], v[164:165], v[24:25]
	v_pk_mul_f32 v[26:27], v[166:167], v[26:27]
	v_pk_fma_f32 v[24:25], v[134:135], v[24:25], v[118:119]
	v_pk_fma_f32 v[26:27], v[136:137], v[26:27], v[120:121]
	v_cvt_pk_bf16_f32 v24, v24, v25
	v_cvt_pk_bf16_f32 v25, v26, v27
	global_store_dwordx2 v[198:199], v[24:25], off offset:-512
	v_pk_mul_f32 v[28:29], v[28:29], v[190:191] op_sel_hi:[1,0]
	v_pk_mul_f32 v[30:31], v[30:31], v[190:191] op_sel_hi:[1,0]
	v_pk_mul_f32 v[28:29], v[168:169], v[28:29]
	v_pk_mul_f32 v[30:31], v[170:171], v[30:31]
	v_pk_fma_f32 v[28:29], v[138:139], v[28:29], v[122:123]
	v_pk_fma_f32 v[30:31], v[140:141], v[30:31], v[124:125]
	v_cvt_pk_bf16_f32 v28, v28, v29
	v_cvt_pk_bf16_f32 v29, v30, v31
	global_store_dwordx2 v[76:77], v[28:29], off offset:-4096
; DI void normmod_phase(const float* xl, const float* xc, const float* g, const float* modl  , int cshift, int cscale, bf16_t* H, int nrows, int gw, int NGW, int lane,
;                       const float* part  , const float* pgate  , float* xc_out) {
;     auto ld = [&](const int row, f32x4 (&v)[4]) __attribute__((always_inline)) -> float {
;         const bool lat = row < ML;
;         const float* xr = lat ? xl + (size_t)row * D : xc + (size_t)(row - ML) * D;
;         float ss = 0.f;
; #pragma unroll
;         for (int j = 0; j < 4; ++j) { v[j] = *(const f32x4*)(xr + lane * 4 + 256 * j);
;             if (part && !lat) {
;                 const size_t po = (size_t)(row - ML) * D + lane * 4 + 256 * j;
;                 const f32x4 p0 = *(const f32x4*)(part + po), p1 = *(const f32x4*)(part + (size_t)MC * D + po), p2 = *(const f32x4*)(part + (size_t)2 * MC * D + po), p3 = *(const f32x4*)(part + (size_t)3 * MC * D + po);
;                 v[j] = v[j] + *(const f32x4*)(pgate + lane * 4 + 256 * j) * ((p0 + p1) + (p2 + p3));
;                 *(f32x4*)(xc_out + po) = v[j]; }
;             ss += (v[j][0] * v[j][0] + v[j][1] * v[j][1]) + (v[j][2] * v[j][2] + v[j][3] * v[j][3]); }
;         return ss; };
;     auto st = [&](const int row, const f32x4 (&v)[4], const float rs) __attribute__((always_inline)) {
;         const float* mp = modl + (size_t)((row < ML) ? (row >> 12) : 16) * 6144;
; #pragma unroll
;         for (int j = 0; j < 4; ++j) { const int c = lane * 4 + 256 * j;
;             const f32x4 gg = *(const f32x4*)(g + c), sh = *(const f32x4*)(mp + cshift * 1024 + c), scl = *(const f32x4*)(mp + cscale * 1024 + c);
;             const f32x4 y = (v[j] * rs) * gg * (scl + 1.f) + sh;
;             u32x2 o; o.x = pk2(y[0], y[1]); o.y = pk2(y[2], y[3]);
;             *(u32x2*)(H + (size_t)row * D + c) = o; } };
;     for (int row = gw * 4; row < (nrows < ML ? nrows : ML); row += NGW * 4) {
;         f32x4 vA[4], vB[4], vC[4], vD[4];
;         float sA = ld(row, vA), sB = ld(row + 1, vB), sC = ld(row + 2, vC), sD = ld(row + 3, vD);
; #pragma unroll
;         for (int o = 1; o < 64; o <<= 1) { sA += __shfl_xor(sA, o); sB += __shfl_xor(sB, o); sC += __shfl_xor(sC, o); sD += __shfl_xor(sD, o); }
;         st(row, vA, rsqrtf(sA * (1.f / D) + EPS)); st(row + 1, vB, rsqrtf(sB * (1.f / D) + EPS));
	global_load_dwordx4 v[16:19], v74, s[4:5] nt
	global_load_dwordx4 v[20:23], v74, s[4:5] offset:1024 nt
	global_load_dwordx4 v[24:27], v74, s[4:5] offset:2048 nt
	global_load_dwordx4 v[28:31], v74, s[4:5] offset:3072 nt
	v_pk_mul_f32 v[32:33], v[32:33], v[192:193] op_sel_hi:[1,0]
	v_pk_mul_f32 v[34:35], v[34:35], v[192:193] op_sel_hi:[1,0]
	v_pk_mul_f32 v[32:33], v[156:157], v[32:33]
	v_pk_mul_f32 v[34:35], v[158:159], v[34:35]
	v_pk_fma_f32 v[32:33], v[126:127], v[32:33], v[110:111]
	v_pk_fma_f32 v[34:35], v[128:129], v[34:35], v[112:113]
	v_cvt_pk_bf16_f32 v32, v32, v33
	v_cvt_pk_bf16_f32 v33, v34, v35
	global_store_dwordx2 v[76:77], v[32:33], off offset:-3584
	v_pk_mul_f32 v[36:37], v[36:37], v[192:193] op_sel_hi:[1,0]
	v_pk_mul_f32 v[38:39], v[38:39], v[192:193] op_sel_hi:[1,0]
	v_pk_mul_f32 v[36:37], v[160:161], v[36:37]
	v_pk_mul_f32 v[38:39], v[162:163], v[38:39]
	v_pk_fma_f32 v[36:37], v[130:131], v[36:37], v[114:115]
	v_pk_fma_f32 v[38:39], v[132:133], v[38:39], v[116:117]
	v_cvt_pk_bf16_f32 v36, v36, v37
	v_cvt_pk_bf16_f32 v37, v38, v39
	global_store_dwordx2 v[76:77], v[36:37], off offset:-3072
	v_pk_mul_f32 v[40:41], v[40:41], v[192:193] op_sel_hi:[1,0]
	v_pk_mul_f32 v[42:43], v[42:43], v[192:193] op_sel_hi:[1,0]
	v_pk_mul_f32 v[40:41], v[164:165], v[40:41]
	v_pk_mul_f32 v[42:43], v[166:167], v[42:43]
	v_pk_fma_f32 v[40:41], v[134:135], v[40:41], v[118:119]
	v_pk_fma_f32 v[42:43], v[136:137], v[42:43], v[120:121]
	v_cvt_pk_bf16_f32 v40, v40, v41
	v_cvt_pk_bf16_f32 v41, v42, v43
	global_store_dwordx2 v[76:77], v[40:41], off offset:-2560
	v_pk_mul_f32 v[44:45], v[44:45], v[192:193] op_sel_hi:[1,0]
	v_pk_mul_f32 v[46:47], v[46:47], v[192:193] op_sel_hi:[1,0]
	v_pk_mul_f32 v[44:45], v[168:169], v[44:45]
	v_pk_mul_f32 v[46:47], v[170:171], v[46:47]
	v_pk_fma_f32 v[44:45], v[138:139], v[44:45], v[122:123]
	v_pk_fma_f32 v[46:47], v[140:141], v[46:47], v[124:125]
	v_cvt_pk_bf16_f32 v44, v44, v45
	v_cvt_pk_bf16_f32 v45, v46, v47
	global_store_dwordx2 v[76:77], v[44:45], off offset:-2048
	v_pk_mul_f32 v[48:49], v[48:49], v[194:195] op_sel_hi:[1,0]
	v_pk_mul_f32 v[50:51], v[50:51], v[194:195] op_sel_hi:[1,0]
	v_pk_mul_f32 v[48:49], v[156:157], v[48:49]
	v_pk_mul_f32 v[50:51], v[158:159], v[50:51]
	v_pk_fma_f32 v[48:49], v[126:127], v[48:49], v[110:111]
	v_pk_fma_f32 v[50:51], v[128:129], v[50:51], v[112:113]
	v_cvt_pk_bf16_f32 v48, v48, v49
	v_cvt_pk_bf16_f32 v49, v50, v51
	global_store_dwordx2 v[76:77], v[48:49], off offset:-1536
	v_pk_mul_f32 v[52:53], v[52:53], v[194:195] op_sel_hi:[1,0]
	v_pk_mul_f32 v[54:55], v[54:55], v[194:195] op_sel_hi:[1,0]
	v_pk_mul_f32 v[52:53], v[160:161], v[52:53]
	v_pk_mul_f32 v[54:55], v[162:163], v[54:55]
	v_pk_fma_f32 v[52:53], v[130:131], v[52:53], v[114:115]
	v_pk_fma_f32 v[54:55], v[132:133], v[54:55], v[116:117]
	v_cvt_pk_bf16_f32 v52, v52, v53
	v_cvt_pk_bf16_f32 v53, v54, v55
	global_store_dwordx2 v[76:77], v[52:53], off offset:-1024
	v_pk_mul_f32 v[56:57], v[56:57], v[194:195] op_sel_hi:[1,0]
	v_pk_mul_f32 v[58:59], v[58:59], v[194:195] op_sel_hi:[1,0]
	v_pk_mul_f32 v[56:57], v[164:165], v[56:57]
	v_pk_mul_f32 v[58:59], v[166:167], v[58:59]
	v_pk_fma_f32 v[56:57], v[134:135], v[56:57], v[118:119]
	v_pk_fma_f32 v[58:59], v[136:137], v[58:59], v[120:121]
	v_cvt_pk_bf16_f32 v56, v56, v57
	v_cvt_pk_bf16_f32 v57, v58, v59
	global_store_dwordx2 v[76:77], v[56:57], off offset:-512
	v_pk_mul_f32 v[60:61], v[60:61], v[194:195] op_sel_hi:[1,0]
	v_pk_mul_f32 v[62:63], v[62:63], v[194:195] op_sel_hi:[1,0]
	v_pk_mul_f32 v[60:61], v[168:169], v[60:61]
	v_pk_mul_f32 v[62:63], v[170:171], v[62:63]
	v_pk_fma_f32 v[60:61], v[138:139], v[60:61], v[122:123]
	v_pk_fma_f32 v[62:63], v[140:141], v[62:63], v[124:125]
	v_cvt_pk_bf16_f32 v60, v60, v61
	v_cvt_pk_bf16_f32 v61, v62, v63
	global_store_dwordx2 v[76:77], v[60:61], off
	s_add_i32 s20, s20, s26
	v_lshl_add_u64 v[76:77], v[76:77], 0, s[48:49]
	s_add_i32 s4, s20, 0xffff
	s_cmp_gt_i32 s4, 0xffff
	s_cbranch_scc1 .Lnm4_nm2_exit
	s_add_i32 s30, s20, 0xffff
	s_ashr_i32 s30, s30, 12
	s_mul_hi_i32 s31, s30, 0x6000
	s_mulk_i32 s30, 0x6000
	s_add_u32 s50, s16, s30
	s_addc_u32 s51, s17, s31
	s_add_u32 s50, s50, 0x3000
	s_addc_u32 s51, s51, 0
	s_add_u32 s52, s50, 0x1000
	s_addc_u32 s53, s51, 0
	global_load_dwordx4 v[110:113], v74, s[50:51]
	global_load_dwordx4 v[114:117], v74, s[50:51] offset:1024
	global_load_dwordx4 v[118:121], v74, s[50:51] offset:2048
	global_load_dwordx4 v[122:125], v74, s[50:51] offset:3072
	global_load_dwordx4 v[126:129], v74, s[52:53]
	global_load_dwordx4 v[130:133], v74, s[52:53] offset:1024
	global_load_dwordx4 v[134:137], v74, s[52:53] offset:2048
	global_load_dwordx4 v[138:141], v74, s[52:53] offset:3072
	s_add_i32 s27, s20, s26
	s_add_i32 s27, s27, 0xffff
	s_cmp_gt_i32 s27, 0xffff
	s_cselect_b32 s30, 0, s46
	s_cselect_b32 s31, 0, s47
	s_add_u32 s44, s44, s30
	s_addc_u32 s45, s45, s31
	s_add_u32 s4, s44, 0x1000
	s_addc_u32 s5, s45, 0
	s_add_u32 s34, s44, 0x2000
	s_addc_u32 s35, s45, 0
	s_add_u32 s54, s44, 0x3000
	s_addc_u32 s55, s45, 0
	global_load_dwordx4 v[32:35], v74, s[34:35] nt
	global_load_dwordx4 v[36:39], v74, s[34:35] offset:1024 nt
	global_load_dwordx4 v[40:43], v74, s[34:35] offset:2048 nt
	global_load_dwordx4 v[44:47], v74, s[34:35] offset:3072 nt
	global_load_dwordx4 v[48:51], v74, s[54:55] nt
	global_load_dwordx4 v[52:55], v74, s[54:55] offset:1024 nt
	global_load_dwordx4 v[56:59], v74, s[54:55] offset:2048 nt
	global_load_dwordx4 v[60:63], v74, s[54:55] offset:3072 nt
	s_mov_b32 s30, 0xfffff000
	s_mov_b32 s31, -1
	v_mov_b32_e32 v178, s68
	v_lshl_add_u64 v[198:199], v[76:77], 0, s[30:31]
	s_waitcnt vmcnt(28)
; DI unsigned pk2(float lo, float hi) { f32x2 v = {lo, hi}; bf16x2_t b = __builtin_convertvector(v, bf16x2_t); return __builtin_bit_cast(unsigned, b); }
; DI void normmod_phase(const float* xl, const float* xc, const float* g, const float* modl  , int cshift, int cscale, bf16_t* H, int nrows, int gw, int NGW, int lane,
;                       const float* part  , const float* pgate  , float* xc_out) {
;     auto ld = [&](const int row, f32x4 (&v)[4]) __attribute__((always_inline)) -> float {
;         const bool lat = row < ML;
;         const float* xr = lat ? xl + (size_t)row * D : xc + (size_t)(row - ML) * D;
;         float ss = 0.f;
; #pragma unroll
;         for (int j = 0; j < 4; ++j) { v[j] = *(const f32x4*)(xr + lane * 4 + 256 * j);
;             if (part && !lat) {
;                 const size_t po = (size_t)(row - ML) * D + lane * 4 + 256 * j;
;                 const f32x4 p0 = *(const f32x4*)(part + po), p1 = *(const f32x4*)(part + (size_t)MC * D + po), p2 = *(const f32x4*)(part + (size_t)2 * MC * D + po), p3 = *(const f32x4*)(part + (size_t)3 * MC * D + po);
;                 v[j] = v[j] + *(const f32x4*)(pgate + lane * 4 + 256 * j) * ((p0 + p1) + (p2 + p3));
;                 *(f32x4*)(xc_out + po) = v[j]; }
;             ss += (v[j][0] * v[j][0] + v[j][1] * v[j][1]) + (v[j][2] * v[j][2] + v[j][3] * v[j][3]); }
;         return ss; };
;     auto st = [&](const int row, const f32x4 (&v)[4], const float rs) __attribute__((always_inline)) {
;         const float* mp = modl + (size_t)((row < ML) ? (row >> 12) : 16) * 6144;
; #pragma unroll
;         for (int j = 0; j < 4; ++j) { const int c = lane * 4 + 256 * j;
;             const f32x4 gg = *(const f32x4*)(g + c), sh = *(const f32x4*)(mp + cshift * 1024 + c), scl = *(const f32x4*)(mp + cscale * 1024 + c);
;             const f32x4 y = (v[j] * rs) * gg * (scl + 1.f) + sh;
;             u32x2 o; o.x = pk2(y[0], y[1]); o.y = pk2(y[2], y[3]);
;             *(u32x2*)(H + (size_t)row * D + c) = o; } };
;     for (int row = gw * 4; row < (nrows < ML ? nrows : ML); row += NGW * 4) {
;         f32x4 vA[4], vB[4], vC[4], vD[4];
;         float sA = ld(row, vA), sB = ld(row + 1, vB), sC = ld(row + 2, vC), sD = ld(row + 3, vD);
; #pragma unroll
;         for (int o = 1; o < 64; o <<= 1) { sA += __shfl_xor(sA, o); sB += __shfl_xor(sB, o); sC += __shfl_xor(sC, o); sD += __shfl_xor(sD, o); }
	v_mul_f32_e32 v176, v1, v1
	v_mul_f32_e32 v177, v3, v3
	v_fmac_f32_e32 v176, v0, v0
	v_fmac_f32_e32 v177, v2, v2
	v_add_f32_e32 v172, v176, v177
	v_mul_f32_e32 v176, v5, v5
	v_mul_f32_e32 v177, v7, v7
	v_fmac_f32_e32 v176, v4, v4
	v_fmac_f32_e32 v177, v6, v6
	v_add_f32_e32 v176, v176, v177
	v_add_f32_e32 v172, v172, v176
	v_mul_f32_e32 v176, v9, v9
	v_mul_f32_e32 v177, v11, v11
	v_fmac_f32_e32 v176, v8, v8
	v_fmac_f32_e32 v177, v10, v10
	v_add_f32_e32 v176, v176, v177
	v_add_f32_e32 v172, v172, v176
	v_mul_f32_e32 v176, v13, v13
	v_mul_f32_e32 v177, v15, v15
	v_fmac_f32_e32 v176, v12, v12
	v_fmac_f32_e32 v177, v14, v14
	v_add_f32_e32 v176, v176, v177
	v_add_f32_e32 v172, v172, v176
	s_waitcnt vmcnt(24)
	v_mul_f32_e32 v176, v17, v17
	v_mul_f32_e32 v177, v19, v19
	v_fmac_f32_e32 v176, v16, v16
	v_fmac_f32_e32 v177, v18, v18
	v_add_f32_e32 v173, v176, v177
	v_mul_f32_e32 v176, v21, v21
	v_mul_f32_e32 v177, v23, v23
	v_fmac_f32_e32 v176, v20, v20
	v_fmac_f32_e32 v177, v22, v22
	v_add_f32_e32 v176, v176, v177
	v_add_f32_e32 v173, v173, v176
	v_mul_f32_e32 v176, v25, v25
	v_mul_f32_e32 v177, v27, v27
	v_fmac_f32_e32 v176, v24, v24
	v_fmac_f32_e32 v177, v26, v26
	v_add_f32_e32 v176, v176, v177
	v_add_f32_e32 v173, v173, v176
	v_mul_f32_e32 v176, v29, v29
	v_mul_f32_e32 v177, v31, v31
	v_fmac_f32_e32 v176, v28, v28
	v_fmac_f32_e32 v177, v30, v30
	v_add_f32_e32 v176, v176, v177
	v_add_f32_e32 v173, v173, v176
	s_waitcnt vmcnt(16)
	v_mul_f32_e32 v176, v215, v215
	v_mul_f32_e32 v177, v217, v217
	v_fmac_f32_e32 v176, v214, v214
	v_fmac_f32_e32 v177, v216, v216
	v_add_f32_e32 v174, v176, v177
	v_mul_f32_e32 v176, v219, v219
	v_mul_f32_e32 v177, v221, v221
	v_fmac_f32_e32 v176, v218, v218
	v_fmac_f32_e32 v177, v220, v220
	v_add_f32_e32 v176, v176, v177
	v_add_f32_e32 v174, v174, v176
	v_mul_f32_e32 v176, v223, v223
	v_mul_f32_e32 v177, v225, v225
	v_fmac_f32_e32 v176, v222, v222
	v_fmac_f32_e32 v177, v224, v224
	v_add_f32_e32 v176, v176, v177
	v_add_f32_e32 v174, v174, v176
	v_mul_f32_e32 v176, v227, v227
	v_mul_f32_e32 v177, v229, v229
	v_fmac_f32_e32 v176, v226, v226
	v_fmac_f32_e32 v177, v228, v228
	v_add_f32_e32 v176, v176, v177
	v_add_f32_e32 v174, v174, v176
	v_mul_f32_e32 v176, v231, v231
	v_mul_f32_e32 v177, v233, v233
	v_fmac_f32_e32 v176, v230, v230
	v_fmac_f32_e32 v177, v232, v232
	v_add_f32_e32 v175, v176, v177
	v_mul_f32_e32 v176, v235, v235
	v_mul_f32_e32 v177, v237, v237
	v_fmac_f32_e32 v176, v234, v234
	v_fmac_f32_e32 v177, v236, v236
	v_add_f32_e32 v176, v176, v177
	v_add_f32_e32 v175, v175, v176
	v_mul_f32_e32 v176, v239, v239
	v_mul_f32_e32 v177, v241, v241
	v_fmac_f32_e32 v176, v238, v238
	v_fmac_f32_e32 v177, v240, v240
	v_add_f32_e32 v176, v176, v177
	v_add_f32_e32 v175, v175, v176
	v_mul_f32_e32 v176, v243, v243
	v_mul_f32_e32 v177, v245, v245
	v_fmac_f32_e32 v176, v242, v242
	v_fmac_f32_e32 v177, v244, v244
	v_add_f32_e32 v176, v176, v177
	v_add_f32_e32 v175, v175, v176
	ds_bpermute_b32 v184, v81, v172
	ds_bpermute_b32 v185, v81, v173
	ds_bpermute_b32 v186, v81, v174
	ds_bpermute_b32 v187, v81, v175
	s_waitcnt lgkmcnt(0)
	v_pk_add_f32 v[172:173], v[172:173], v[184:185]
	v_pk_add_f32 v[174:175], v[174:175], v[186:187]
	ds_bpermute_b32 v184, v82, v172
	ds_bpermute_b32 v185, v82, v173
	ds_bpermute_b32 v186, v82, v174
	ds_bpermute_b32 v187, v82, v175
	s_waitcnt lgkmcnt(0)
	v_pk_add_f32 v[172:173], v[172:173], v[184:185]
	v_pk_add_f32 v[174:175], v[174:175], v[186:187]
	ds_bpermute_b32 v184, v83, v172
	ds_bpermute_b32 v185, v83, v173
	ds_bpermute_b32 v186, v83, v174
	ds_bpermute_b32 v187, v83, v175
	s_waitcnt lgkmcnt(0)
	v_pk_add_f32 v[172:173], v[172:173], v[184:185]
	v_pk_add_f32 v[174:175], v[174:175], v[186:187]
	ds_bpermute_b32 v184, v84, v172
	ds_bpermute_b32 v185, v84, v173
	ds_bpermute_b32 v186, v84, v174
	ds_bpermute_b32 v187, v84, v175
	s_waitcnt lgkmcnt(0)
	v_pk_add_f32 v[172:173], v[172:173], v[184:185]
	v_pk_add_f32 v[174:175], v[174:175], v[186:187]
	ds_bpermute_b32 v184, v85, v172
	ds_bpermute_b32 v185, v85, v173
	ds_bpermute_b32 v186, v85, v174
	ds_bpermute_b32 v187, v85, v175
	s_waitcnt lgkmcnt(0)
	v_pk_add_f32 v[172:173], v[172:173], v[184:185]
	v_pk_add_f32 v[174:175], v[174:175], v[186:187]
	ds_bpermute_b32 v184, v86, v172
	ds_bpermute_b32 v185, v86, v173
	ds_bpermute_b32 v186, v86, v174
	ds_bpermute_b32 v187, v86, v175
	s_waitcnt lgkmcnt(0)
	v_pk_add_f32 v[172:173], v[172:173], v[184:185]
	v_pk_add_f32 v[174:175], v[174:175], v[186:187]
	v_fma_f32 v172, v172, s66, v178
	v_fma_f32 v173, v173, s66, v178
	v_fma_f32 v174, v174, s66, v178
	v_fma_f32 v175, v175, s66, v178
	v_mul_f32_e32 v184, 0x4b800000, v172
	v_mul_f32_e32 v185, 0x4b800000, v173
	v_mul_f32_e32 v186, 0x4b800000, v174
	v_mul_f32_e32 v187, 0x4b800000, v175
	s_waitcnt vmcnt(8)
; DI unsigned pk2(float lo, float hi) { f32x2 v = {lo, hi}; bf16x2_t b = __builtin_convertvector(v, bf16x2_t); return __builtin_bit_cast(unsigned, b); }
; DI void normmod_phase(const float* xl, const float* xc, const float* g, const float* modl  , int cshift, int cscale, bf16_t* H, int nrows, int gw, int NGW, int lane,
;                       const float* part  , const float* pgate  , float* xc_out) {
;     ...
;     auto st = [&](const int row, const f32x4 (&v)[4], const float rs) __attribute__((always_inline)) {
;         const float* mp = modl + (size_t)((row < ML) ? (row >> 12) : 16) * 6144;
; #pragma unroll
;         for (int j = 0; j < 4; ++j) { const int c = lane * 4 + 256 * j;
;             const f32x4 gg = *(const f32x4*)(g + c), sh = *(const f32x4*)(mp + cshift * 1024 + c), scl = *(const f32x4*)(mp + cscale * 1024 + c);
;             const f32x4 y = (v[j] * rs) * gg * (scl + 1.f) + sh;
;             u32x2 o; o.x = pk2(y[0], y[1]); o.y = pk2(y[2], y[3]);
;             *(u32x2*)(H + (size_t)row * D + c) = o; } };
;     for (int row = gw * 4; row < (nrows < ML ? nrows : ML); row += NGW * 4) {
;         f32x4 vA[4], vB[4], vC[4], vD[4];
;         float sA = ld(row, vA), sB = ld(row + 1, vB), sC = ld(row + 2, vC), sD = ld(row + 3, vD);
; #pragma unroll
;         for (int o = 1; o < 64; o <<= 1) { sA += __shfl_xor(sA, o); sB += __shfl_xor(sB, o); sC += __shfl_xor(sC, o); sD += __shfl_xor(sD, o); }
;         st(row, vA, rsqrtf(sA * (1.f / D) + EPS)); st(row + 1, vB, rsqrtf(sB * (1.f / D) + EPS));
;         st(row + 2, vC, rsqrtf(sC * (1.f / D) + EPS)); st(row + 3, vD, rsqrtf(sD * (1.f / D) + EPS));
	v_cmp_gt_f32_e64 s[50:51], s62, v172
	v_cmp_gt_f32_e64 s[52:53], s62, v173
	v_cmp_gt_f32_e64 s[30:31], s62, v174
	v_cmp_gt_f32_e32 vcc, s62, v175
	s_nop 1
	v_cndmask_b32_e64 v172, v172, v184, s[50:51]
	v_cndmask_b32_e64 v173, v173, v185, s[52:53]
	v_cndmask_b32_e64 v174, v174, v186, s[30:31]
	v_cndmask_b32_e32 v175, v175, v187, vcc
	v_rsq_f32_e32 v172, v172
	v_rsq_f32_e32 v173, v173
	v_rsq_f32_e32 v174, v174
	v_rsq_f32_e32 v175, v175
	s_nop 0
	v_mul_f32_e32 v184, 0x45800000, v172
	v_mul_f32_e32 v185, 0x45800000, v173
	v_mul_f32_e32 v186, 0x45800000, v174
	v_mul_f32_e32 v187, 0x45800000, v175
	v_cndmask_b32_e64 v188, v172, v184, s[50:51]
	v_cndmask_b32_e64 v190, v173, v185, s[52:53]
	v_cndmask_b32_e64 v192, v174, v186, s[30:31]
	v_cndmask_b32_e32 v194, v175, v187, vcc
	v_pk_add_f32 v[126:127], v[126:127], 1.0 op_sel_hi:[1,0]
	v_pk_add_f32 v[128:129], v[128:129], 1.0 op_sel_hi:[1,0]
	v_pk_add_f32 v[130:131], v[130:131], 1.0 op_sel_hi:[1,0]
	v_pk_add_f32 v[132:133], v[132:133], 1.0 op_sel_hi:[1,0]
	v_pk_add_f32 v[134:135], v[134:135], 1.0 op_sel_hi:[1,0]
	v_pk_add_f32 v[136:137], v[136:137], 1.0 op_sel_hi:[1,0]
	v_pk_add_f32 v[138:139], v[138:139], 1.0 op_sel_hi:[1,0]
	v_pk_add_f32 v[140:141], v[140:141], 1.0 op_sel_hi:[1,0]
	v_pk_mul_f32 v[0:1], v[0:1], v[188:189] op_sel_hi:[1,0]
	v_pk_mul_f32 v[2:3], v[2:3], v[188:189] op_sel_hi:[1,0]
	v_pk_mul_f32 v[0:1], v[156:157], v[0:1]
	v_pk_mul_f32 v[2:3], v[158:159], v[2:3]
	v_pk_fma_f32 v[0:1], v[126:127], v[0:1], v[110:111]
	v_pk_fma_f32 v[2:3], v[128:129], v[2:3], v[112:113]
	v_cvt_pk_bf16_f32 v0, v0, v1
	v_cvt_pk_bf16_f32 v1, v2, v3
	global_store_dwordx2 v[198:199], v[0:1], off offset:-3584
	v_pk_mul_f32 v[4:5], v[4:5], v[188:189] op_sel_hi:[1,0]
	v_pk_mul_f32 v[6:7], v[6:7], v[188:189] op_sel_hi:[1,0]
	v_pk_mul_f32 v[4:5], v[160:161], v[4:5]
	v_pk_mul_f32 v[6:7], v[162:163], v[6:7]
	v_pk_fma_f32 v[4:5], v[130:131], v[4:5], v[114:115]
	v_pk_fma_f32 v[6:7], v[132:133], v[6:7], v[116:117]
	v_cvt_pk_bf16_f32 v4, v4, v5
	v_cvt_pk_bf16_f32 v5, v6, v7
	global_store_dwordx2 v[198:199], v[4:5], off offset:-3072
	v_pk_mul_f32 v[8:9], v[8:9], v[188:189] op_sel_hi:[1,0]
	v_pk_mul_f32 v[10:11], v[10:11], v[188:189] op_sel_hi:[1,0]
	v_pk_mul_f32 v[8:9], v[164:165], v[8:9]
	v_pk_mul_f32 v[10:11], v[166:167], v[10:11]
	v_pk_fma_f32 v[8:9], v[134:135], v[8:9], v[118:119]
	v_pk_fma_f32 v[10:11], v[136:137], v[10:11], v[120:121]
	v_cvt_pk_bf16_f32 v8, v8, v9
	v_cvt_pk_bf16_f32 v9, v10, v11
	global_store_dwordx2 v[198:199], v[8:9], off offset:-2560
	v_pk_mul_f32 v[12:13], v[12:13], v[188:189] op_sel_hi:[1,0]
	v_pk_mul_f32 v[14:15], v[14:15], v[188:189] op_sel_hi:[1,0]
	v_pk_mul_f32 v[12:13], v[168:169], v[12:13]
	v_pk_mul_f32 v[14:15], v[170:171], v[14:15]
	v_pk_fma_f32 v[12:13], v[138:139], v[12:13], v[122:123]
	v_pk_fma_f32 v[14:15], v[140:141], v[14:15], v[124:125]
	v_cvt_pk_bf16_f32 v12, v12, v13
	v_cvt_pk_bf16_f32 v13, v14, v15
	global_store_dwordx2 v[198:199], v[12:13], off offset:-2048
	global_load_dwordx4 v[0:3], v74, s[44:45] nt
	global_load_dwordx4 v[4:7], v74, s[44:45] offset:1024 nt
	global_load_dwordx4 v[8:11], v74, s[44:45] offset:2048 nt
	global_load_dwordx4 v[12:15], v74, s[44:45] offset:3072 nt
	v_pk_mul_f32 v[16:17], v[16:17], v[190:191] op_sel_hi:[1,0]
	v_pk_mul_f32 v[18:19], v[18:19], v[190:191] op_sel_hi:[1,0]
	v_pk_mul_f32 v[16:17], v[156:157], v[16:17]
	v_pk_mul_f32 v[18:19], v[158:159], v[18:19]
	v_pk_fma_f32 v[16:17], v[126:127], v[16:17], v[110:111]
	v_pk_fma_f32 v[18:19], v[128:129], v[18:19], v[112:113]
	v_cvt_pk_bf16_f32 v16, v16, v17
	v_cvt_pk_bf16_f32 v17, v18, v19
	global_store_dwordx2 v[198:199], v[16:17], off offset:-1536
	v_pk_mul_f32 v[20:21], v[20:21], v[190:191] op_sel_hi:[1,0]
	v_pk_mul_f32 v[22:23], v[22:23], v[190:191] op_sel_hi:[1,0]
	v_pk_mul_f32 v[20:21], v[160:161], v[20:21]
	v_pk_mul_f32 v[22:23], v[162:163], v[22:23]
	v_pk_fma_f32 v[20:21], v[130:131], v[20:21], v[114:115]
	v_pk_fma_f32 v[22:23], v[132:133], v[22:23], v[116:117]
	v_cvt_pk_bf16_f32 v20, v20, v21
	v_cvt_pk_bf16_f32 v21, v22, v23
	global_store_dwordx2 v[198:199], v[20:21], off offset:-1024
	v_pk_mul_f32 v[24:25], v[24:25], v[190:191] op_sel_hi:[1,0]
	v_pk_mul_f32 v[26:27], v[26:27], v[190:191] op_sel_hi:[1,0]
	v_pk_mul_f32 v[24:25], v[164:165], v[24:25]
	v_pk_mul_f32 v[26:27], v[166:167], v[26:27]
	v_pk_fma_f32 v[24:25], v[134:135], v[24:25], v[118:119]
	v_pk_fma_f32 v[26:27], v[136:137], v[26:27], v[120:121]
	v_cvt_pk_bf16_f32 v24, v24, v25
	v_cvt_pk_bf16_f32 v25, v26, v27
	global_store_dwordx2 v[198:199], v[24:25], off offset:-512
	v_pk_mul_f32 v[28:29], v[28:29], v[190:191] op_sel_hi:[1,0]
	v_pk_mul_f32 v[30:31], v[30:31], v[190:191] op_sel_hi:[1,0]
	v_pk_mul_f32 v[28:29], v[168:169], v[28:29]
	v_pk_mul_f32 v[30:31], v[170:171], v[30:31]
	v_pk_fma_f32 v[28:29], v[138:139], v[28:29], v[122:123]
	v_pk_fma_f32 v[30:31], v[140:141], v[30:31], v[124:125]
	v_cvt_pk_bf16_f32 v28, v28, v29
	v_cvt_pk_bf16_f32 v29, v30, v31
	global_store_dwordx2 v[76:77], v[28:29], off offset:-4096
	global_load_dwordx4 v[16:19], v74, s[4:5] nt
	global_load_dwordx4 v[20:23], v74, s[4:5] offset:1024 nt
	global_load_dwordx4 v[24:27], v74, s[4:5] offset:2048 nt
	global_load_dwordx4 v[28:31], v74, s[4:5] offset:3072 nt
	v_pk_mul_f32 v[214:215], v[214:215], v[192:193] op_sel_hi:[1,0]
; DI unsigned pk2(float lo, float hi) { f32x2 v = {lo, hi}; bf16x2_t b = __builtin_convertvector(v, bf16x2_t); return __builtin_bit_cast(unsigned, b); }
; DI void normmod_phase(const float* xl, const float* xc, const float* g, const float* modl  , int cshift, int cscale, bf16_t* H, int nrows, int gw, int NGW, int lane,
;                       const float* part  , const float* pgate  , float* xc_out) {
;     ...
;     auto st = [&](const int row, const f32x4 (&v)[4], const float rs) __attribute__((always_inline)) {
;         const float* mp = modl + (size_t)((row < ML) ? (row >> 12) : 16) * 6144;
; #pragma unroll
;         for (int j = 0; j < 4; ++j) { const int c = lane * 4 + 256 * j;
;             const f32x4 gg = *(const f32x4*)(g + c), sh = *(const f32x4*)(mp + cshift * 1024 + c), scl = *(const f32x4*)(mp + cscale * 1024 + c);
;             const f32x4 y = (v[j] * rs) * gg * (scl + 1.f) + sh;
;             u32x2 o; o.x = pk2(y[0], y[1]); o.y = pk2(y[2], y[3]);
;             *(u32x2*)(H + (size_t)row * D + c) = o; } };
;     for (int row = gw * 4; row < (nrows < ML ? nrows : ML); row += NGW * 4) {
;         f32x4 vA[4], vB[4], vC[4], vD[4];
;         float sA = ld(row, vA), sB = ld(row + 1, vB), sC = ld(row + 2, vC), sD = ld(row + 3, vD);
; #pragma unroll
;         for (int o = 1; o < 64; o <<= 1) { sA += __shfl_xor(sA, o); sB += __shfl_xor(sB, o); sC += __shfl_xor(sC, o); sD += __shfl_xor(sD, o); }
;         st(row, vA, rsqrtf(sA * (1.f / D) + EPS)); st(row + 1, vB, rsqrtf(sB * (1.f / D) + EPS));
;         st(row + 2, vC, rsqrtf(sC * (1.f / D) + EPS)); st(row + 3, vD, rsqrtf(sD * (1.f / D) + EPS));
;     }
;     for (int row = ML + gw * 2; row < nrows; row += NGW * 2) {
	v_pk_mul_f32 v[216:217], v[216:217], v[192:193] op_sel_hi:[1,0]
	v_pk_mul_f32 v[214:215], v[156:157], v[214:215]
	v_pk_mul_f32 v[216:217], v[158:159], v[216:217]
	v_pk_fma_f32 v[214:215], v[126:127], v[214:215], v[110:111]
	v_pk_fma_f32 v[216:217], v[128:129], v[216:217], v[112:113]
	v_cvt_pk_bf16_f32 v214, v214, v215
	v_cvt_pk_bf16_f32 v215, v216, v217
	global_store_dwordx2 v[76:77], v[214:215], off offset:-3584
	v_pk_mul_f32 v[218:219], v[218:219], v[192:193] op_sel_hi:[1,0]
	v_pk_mul_f32 v[220:221], v[220:221], v[192:193] op_sel_hi:[1,0]
	v_pk_mul_f32 v[218:219], v[160:161], v[218:219]
	v_pk_mul_f32 v[220:221], v[162:163], v[220:221]
	v_pk_fma_f32 v[218:219], v[130:131], v[218:219], v[114:115]
	v_pk_fma_f32 v[220:221], v[132:133], v[220:221], v[116:117]
	v_cvt_pk_bf16_f32 v218, v218, v219
	v_cvt_pk_bf16_f32 v219, v220, v221
	global_store_dwordx2 v[76:77], v[218:219], off offset:-3072
	v_pk_mul_f32 v[222:223], v[222:223], v[192:193] op_sel_hi:[1,0]
	v_pk_mul_f32 v[224:225], v[224:225], v[192:193] op_sel_hi:[1,0]
	v_pk_mul_f32 v[222:223], v[164:165], v[222:223]
	v_pk_mul_f32 v[224:225], v[166:167], v[224:225]
	v_pk_fma_f32 v[222:223], v[134:135], v[222:223], v[118:119]
	v_pk_fma_f32 v[224:225], v[136:137], v[224:225], v[120:121]
	v_cvt_pk_bf16_f32 v222, v222, v223
	v_cvt_pk_bf16_f32 v223, v224, v225
	global_store_dwordx2 v[76:77], v[222:223], off offset:-2560
	v_pk_mul_f32 v[226:227], v[226:227], v[192:193] op_sel_hi:[1,0]
	v_pk_mul_f32 v[228:229], v[228:229], v[192:193] op_sel_hi:[1,0]
	v_pk_mul_f32 v[226:227], v[168:169], v[226:227]
	v_pk_mul_f32 v[228:229], v[170:171], v[228:229]
	v_pk_fma_f32 v[226:227], v[138:139], v[226:227], v[122:123]
	v_pk_fma_f32 v[228:229], v[140:141], v[228:229], v[124:125]
	v_cvt_pk_bf16_f32 v226, v226, v227
	v_cvt_pk_bf16_f32 v227, v228, v229
	global_store_dwordx2 v[76:77], v[226:227], off offset:-2048
	v_pk_mul_f32 v[230:231], v[230:231], v[194:195] op_sel_hi:[1,0]
	v_pk_mul_f32 v[232:233], v[232:233], v[194:195] op_sel_hi:[1,0]
	v_pk_mul_f32 v[230:231], v[156:157], v[230:231]
	v_pk_mul_f32 v[232:233], v[158:159], v[232:233]
	v_pk_fma_f32 v[230:231], v[126:127], v[230:231], v[110:111]
	v_pk_fma_f32 v[232:233], v[128:129], v[232:233], v[112:113]
	v_cvt_pk_bf16_f32 v230, v230, v231
	v_cvt_pk_bf16_f32 v231, v232, v233
	global_store_dwordx2 v[76:77], v[230:231], off offset:-1536
	v_pk_mul_f32 v[234:235], v[234:235], v[194:195] op_sel_hi:[1,0]
	v_pk_mul_f32 v[236:237], v[236:237], v[194:195] op_sel_hi:[1,0]
	v_pk_mul_f32 v[234:235], v[160:161], v[234:235]
	v_pk_mul_f32 v[236:237], v[162:163], v[236:237]
	v_pk_fma_f32 v[234:235], v[130:131], v[234:235], v[114:115]
	v_pk_fma_f32 v[236:237], v[132:133], v[236:237], v[116:117]
	v_cvt_pk_bf16_f32 v234, v234, v235
	v_cvt_pk_bf16_f32 v235, v236, v237
	global_store_dwordx2 v[76:77], v[234:235], off offset:-1024
	v_pk_mul_f32 v[238:239], v[238:239], v[194:195] op_sel_hi:[1,0]
	v_pk_mul_f32 v[240:241], v[240:241], v[194:195] op_sel_hi:[1,0]
	v_pk_mul_f32 v[238:239], v[164:165], v[238:239]
	v_pk_mul_f32 v[240:241], v[166:167], v[240:241]
	v_pk_fma_f32 v[238:239], v[134:135], v[238:239], v[118:119]
	v_pk_fma_f32 v[240:241], v[136:137], v[240:241], v[120:121]
	v_cvt_pk_bf16_f32 v238, v238, v239
	v_cvt_pk_bf16_f32 v239, v240, v241
	global_store_dwordx2 v[76:77], v[238:239], off offset:-512
	v_pk_mul_f32 v[242:243], v[242:243], v[194:195] op_sel_hi:[1,0]
	v_pk_mul_f32 v[244:245], v[244:245], v[194:195] op_sel_hi:[1,0]
	v_pk_mul_f32 v[242:243], v[168:169], v[242:243]
	v_pk_mul_f32 v[244:245], v[170:171], v[244:245]
	v_pk_fma_f32 v[242:243], v[138:139], v[242:243], v[122:123]
	v_pk_fma_f32 v[244:245], v[140:141], v[244:245], v[124:125]
	v_cvt_pk_bf16_f32 v242, v242, v243
	v_cvt_pk_bf16_f32 v243, v244, v245
	global_store_dwordx2 v[76:77], v[242:243], off
	s_add_i32 s20, s20, s26
	v_lshl_add_u64 v[76:77], v[76:77], 0, s[48:49]
	s_add_i32 s4, s20, 0xffff
	s_cmp_gt_i32 s4, 0xffff
	s_cbranch_scc0 .LBB0_317
.Lnm4_nm2_exit:
	s_waitcnt vmcnt(0)
.LBB0_353:
	s_lshl_b32 s20, s36, 1
	s_add_i32 s4, s20, 0x10000
	s_cmp_ge_i32 s4, s24
	s_cbranch_scc1 .LBB0_380
	v_xor_b32_e32 v0, 1, v210
	v_cmp_lt_i32_e32 vcc, v0, v250
	s_ashr_i32 s5, s4, 31
	s_lshl_b32 s26, s33, 4
	v_cndmask_b32_e32 v0, v210, v0, vcc
	v_lshlrev_b32_e32 v34, 2, v0
	v_xor_b32_e32 v0, 2, v210
	v_cmp_lt_i32_e32 vcc, v0, v250
	s_lshl_b64 s[30:31], s[4:5], 12
	s_add_u32 s44, s10, s30
	v_cndmask_b32_e32 v0, v210, v0, vcc
	v_cmp_lt_i32_e32 vcc, v251, v250
	v_lshlrev_b32_e32 v35, 2, v0
	s_addc_u32 s45, s11, s31
	v_cndmask_b32_e32 v0, v210, v251, vcc
	v_lshlrev_b32_e32 v36, 2, v0
	v_xor_b32_e32 v0, 8, v210
	v_cmp_lt_i32_e32 vcc, v0, v250
	s_ashr_i32 s27, s26, 31
	s_lshl_b64 s[46:47], s[26:27], 12
	v_cndmask_b32_e32 v0, v210, v0, vcc
	v_lshlrev_b32_e32 v37, 2, v0
	v_xor_b32_e32 v0, 16, v210
	v_cmp_lt_i32_e32 vcc, v0, v250
	s_lshl_b64 s[4:5], s[4:5], 11
	v_readlane_b32 s12, v254, 28
	v_cndmask_b32_e32 v0, v210, v0, vcc
	s_add_u32 s25, s12, s78
	v_readlane_b32 s12, v254, 29
	v_lshlrev_b32_e32 v38, 2, v0
	v_xor_b32_e32 v0, 32, v210
	s_addc_u32 s30, s12, s79
	v_cmp_lt_i32_e32 vcc, v0, v250
	s_add_u32 s4, s25, s4
	v_lshlrev_b32_e32 v148, 3, v152
	v_cndmask_b32_e32 v0, v210, v0, vcc
	s_addc_u32 s5, s30, s5
	v_lshlrev_b32_e32 v39, 2, v0
	v_lshl_add_u64 v[32:33], s[4:5], 0, v[148:149]
	s_lshl_b64 s[48:49], s[26:27], 11
	s_branch .LBB0_356

; DI unsigned pk2(float lo, float hi) { f32x2 v = {lo, hi}; bf16x2_t b = __builtin_convertvector(v, bf16x2_t); return __builtin_bit_cast(unsigned, b); }
; DI void normmod_phase(const float* xl, const float* xc, const float* g, const float* modl  , int cshift, int cscale, bf16_t* H, int nrows, int gw, int NGW, int lane,
;                       const float* part  , const float* pgate  , float* xc_out) {
;     auto ld = [&](const int row, f32x4 (&v)[4]) __attribute__((always_inline)) -> float {
;         const bool lat = row < ML;
;         const float* xr = lat ? xl + (size_t)row * D : xc + (size_t)(row - ML) * D;
;         float ss = 0.f;
; #pragma unroll
;         for (int j = 0; j < 4; ++j) { v[j] = *(const f32x4*)(xr + lane * 4 + 256 * j);
;             if (part && !lat) {
;                 const size_t po = (size_t)(row - ML) * D + lane * 4 + 256 * j;
;                 const f32x4 p0 = *(const f32x4*)(part + po), p1 = *(const f32x4*)(part + (size_t)MC * D + po), p2 = *(const f32x4*)(part + (size_t)2 * MC * D + po), p3 = *(const f32x4*)(part + (size_t)3 * MC * D + po);
;                 v[j] = v[j] + *(const f32x4*)(pgate + lane * 4 + 256 * j) * ((p0 + p1) + (p2 + p3));
;                 *(f32x4*)(xc_out + po) = v[j]; }
;             ss += (v[j][0] * v[j][0] + v[j][1] * v[j][1]) + (v[j][2] * v[j][2] + v[j][3] * v[j][3]); }
;         return ss; };
;     auto st = [&](const int row, const f32x4 (&v)[4], const float rs) __attribute__((always_inline)) {
;         const float* mp = modl + (size_t)((row < ML) ? (row >> 12) : 16) * 6144;
; #pragma unroll
;         for (int j = 0; j < 4; ++j) { const int c = lane * 4 + 256 * j;
;             const f32x4 gg = *(const f32x4*)(g + c), sh = *(const f32x4*)(mp + cshift * 1024 + c), scl = *(const f32x4*)(mp + cscale * 1024 + c);
;             const f32x4 y = (v[j] * rs) * gg * (scl + 1.f) + sh;
;             u32x2 o; o.x = pk2(y[0], y[1]); o.y = pk2(y[2], y[3]);
;             *(u32x2*)(H + (size_t)row * D + c) = o; } };
;     for (int row = gw * 4; row < (nrows < ML ? nrows : ML); row += NGW * 4) {
;         f32x4 vA[4], vB[4], vC[4], vD[4];
;         float sA = ld(row, vA), sB = ld(row + 1, vB), sC = ld(row + 2, vC), sD = ld(row + 3, vD);
; #pragma unroll
;         for (int o = 1; o < 64; o <<= 1) { sA += __shfl_xor(sA, o); sB += __shfl_xor(sB, o); sC += __shfl_xor(sC, o); sD += __shfl_xor(sD, o); }
.LBB0_557:
	s_add_i32 s30, s20, 0xffff
	s_ashr_i32 s30, s30, 12
	s_mul_hi_i32 s31, s30, 0x6000
	s_mulk_i32 s30, 0x6000
	s_add_u32 s50, s16, s30
	s_addc_u32 s51, s17, s31
	s_add_u32 s52, s50, 0x1000
	s_addc_u32 s53, s51, 0
	global_load_dwordx4 v[110:113], v76, s[50:51]
	global_load_dwordx4 v[114:117], v76, s[50:51] offset:1024
	global_load_dwordx4 v[118:121], v76, s[50:51] offset:2048
	global_load_dwordx4 v[122:125], v76, s[50:51] offset:3072
	global_load_dwordx4 v[126:129], v76, s[52:53]
	global_load_dwordx4 v[130:133], v76, s[52:53] offset:1024
	global_load_dwordx4 v[134:137], v76, s[52:53] offset:2048
	global_load_dwordx4 v[138:141], v76, s[52:53] offset:3072
	s_add_i32 s27, s20, s26
	s_add_i32 s27, s27, 0xffff
	s_cmp_gt_i32 s27, 0xffff
	s_cselect_b32 s30, 0, s44
	s_cselect_b32 s31, 0, s45
	s_add_u32 s42, s42, s30
	s_addc_u32 s43, s43, s31
	s_add_u32 s4, s42, 0x1000
	s_addc_u32 s5, s43, 0
	s_add_u32 s24, s42, 0x2000
	s_addc_u32 s25, s43, 0
	s_add_u32 s48, s42, 0x3000
	s_addc_u32 s49, s43, 0
	global_load_dwordx4 v[214:217], v76, s[24:25] nt
	global_load_dwordx4 v[218:221], v76, s[24:25] offset:1024 nt
	global_load_dwordx4 v[222:225], v76, s[24:25] offset:2048 nt
	global_load_dwordx4 v[226:229], v76, s[24:25] offset:3072 nt
	global_load_dwordx4 v[230:233], v76, s[48:49] nt
	global_load_dwordx4 v[234:237], v76, s[48:49] offset:1024 nt
	global_load_dwordx4 v[238:241], v76, s[48:49] offset:2048 nt
	global_load_dwordx4 v[242:245], v76, s[48:49] offset:3072 nt
	s_mov_b32 s30, 0xfffff000
	s_mov_b32 s31, -1
	v_mov_b32_e32 v178, s36
	v_lshl_add_u64 v[198:199], v[78:79], 0, s[30:31]
	s_waitcnt vmcnt(28)
	v_mul_f32_e32 v176, v1, v1
	v_mul_f32_e32 v177, v3, v3
	v_fmac_f32_e32 v176, v0, v0
	v_fmac_f32_e32 v177, v2, v2
	v_add_f32_e32 v172, v176, v177
	v_mul_f32_e32 v176, v5, v5
	v_mul_f32_e32 v177, v7, v7
	v_fmac_f32_e32 v176, v4, v4
	v_fmac_f32_e32 v177, v6, v6
	v_add_f32_e32 v176, v176, v177
	v_add_f32_e32 v172, v172, v176
	v_mul_f32_e32 v176, v9, v9
	v_mul_f32_e32 v177, v11, v11
	v_fmac_f32_e32 v176, v8, v8
	v_fmac_f32_e32 v177, v10, v10
	v_add_f32_e32 v176, v176, v177
	v_add_f32_e32 v172, v172, v176
	v_mul_f32_e32 v176, v13, v13
	v_mul_f32_e32 v177, v15, v15
	v_fmac_f32_e32 v176, v12, v12
	v_fmac_f32_e32 v177, v14, v14
	v_add_f32_e32 v176, v176, v177
	v_add_f32_e32 v172, v172, v176
	s_waitcnt vmcnt(24)
	v_mul_f32_e32 v176, v17, v17
	v_mul_f32_e32 v177, v19, v19
	v_fmac_f32_e32 v176, v16, v16
	v_fmac_f32_e32 v177, v18, v18
	v_add_f32_e32 v173, v176, v177
	v_mul_f32_e32 v176, v21, v21
	v_mul_f32_e32 v177, v23, v23
	v_fmac_f32_e32 v176, v20, v20
	v_fmac_f32_e32 v177, v22, v22
	v_add_f32_e32 v176, v176, v177
	v_add_f32_e32 v173, v173, v176
	v_mul_f32_e32 v176, v25, v25
	v_mul_f32_e32 v177, v27, v27
	v_fmac_f32_e32 v176, v24, v24
	v_fmac_f32_e32 v177, v26, v26
	v_add_f32_e32 v176, v176, v177
	v_add_f32_e32 v173, v173, v176
	v_mul_f32_e32 v176, v29, v29
	v_mul_f32_e32 v177, v31, v31
	v_fmac_f32_e32 v176, v28, v28
	v_fmac_f32_e32 v177, v30, v30
	v_add_f32_e32 v176, v176, v177
	v_add_f32_e32 v173, v173, v176
	s_waitcnt vmcnt(16)
	v_mul_f32_e32 v176, v33, v33
	v_mul_f32_e32 v177, v35, v35
	v_fmac_f32_e32 v176, v32, v32
	v_fmac_f32_e32 v177, v34, v34
	v_add_f32_e32 v174, v176, v177
	v_mul_f32_e32 v176, v37, v37
	v_mul_f32_e32 v177, v39, v39
	v_fmac_f32_e32 v176, v36, v36
	v_fmac_f32_e32 v177, v38, v38
	v_add_f32_e32 v176, v176, v177
	v_add_f32_e32 v174, v174, v176
	v_mul_f32_e32 v176, v41, v41
	v_mul_f32_e32 v177, v43, v43
	v_fmac_f32_e32 v176, v40, v40
	v_fmac_f32_e32 v177, v42, v42
	v_add_f32_e32 v176, v176, v177
	v_add_f32_e32 v174, v174, v176
	v_mul_f32_e32 v176, v45, v45
	v_mul_f32_e32 v177, v47, v47
	v_fmac_f32_e32 v176, v44, v44
	v_fmac_f32_e32 v177, v46, v46
	v_add_f32_e32 v176, v176, v177
	v_add_f32_e32 v174, v174, v176
	v_mul_f32_e32 v176, v49, v49
	v_mul_f32_e32 v177, v51, v51
	v_fmac_f32_e32 v176, v48, v48
	v_fmac_f32_e32 v177, v50, v50
	v_add_f32_e32 v175, v176, v177
	v_mul_f32_e32 v176, v53, v53
	v_mul_f32_e32 v177, v55, v55
	v_fmac_f32_e32 v176, v52, v52
	v_fmac_f32_e32 v177, v54, v54
	v_add_f32_e32 v176, v176, v177
	v_add_f32_e32 v175, v175, v176
	v_mul_f32_e32 v176, v57, v57
	v_mul_f32_e32 v177, v59, v59
	v_fmac_f32_e32 v176, v56, v56
	v_fmac_f32_e32 v177, v58, v58
	v_add_f32_e32 v176, v176, v177
	v_add_f32_e32 v175, v175, v176
	v_mul_f32_e32 v176, v61, v61
	v_mul_f32_e32 v177, v63, v63
	v_fmac_f32_e32 v176, v60, v60
	v_fmac_f32_e32 v177, v62, v62
	v_add_f32_e32 v176, v176, v177
	v_add_f32_e32 v175, v175, v176
	ds_bpermute_b32 v184, v83, v172
	ds_bpermute_b32 v185, v83, v173
	ds_bpermute_b32 v186, v83, v174
	ds_bpermute_b32 v187, v83, v175
	s_waitcnt lgkmcnt(0)
	v_pk_add_f32 v[172:173], v[172:173], v[184:185]
	v_pk_add_f32 v[174:175], v[174:175], v[186:187]
	ds_bpermute_b32 v184, v84, v172
	ds_bpermute_b32 v185, v84, v173
	ds_bpermute_b32 v186, v84, v174
	ds_bpermute_b32 v187, v84, v175
	s_waitcnt lgkmcnt(0)
	v_pk_add_f32 v[172:173], v[172:173], v[184:185]
	v_pk_add_f32 v[174:175], v[174:175], v[186:187]
	ds_bpermute_b32 v184, v85, v172
	ds_bpermute_b32 v185, v85, v173
	ds_bpermute_b32 v186, v85, v174
	ds_bpermute_b32 v187, v85, v175
	s_waitcnt lgkmcnt(0)
	v_pk_add_f32 v[172:173], v[172:173], v[184:185]
	v_pk_add_f32 v[174:175], v[174:175], v[186:187]
	ds_bpermute_b32 v184, v86, v172
	ds_bpermute_b32 v185, v86, v173
	ds_bpermute_b32 v186, v86, v174
	ds_bpermute_b32 v187, v86, v175
	s_waitcnt lgkmcnt(0)
	v_pk_add_f32 v[172:173], v[172:173], v[184:185]
	v_pk_add_f32 v[174:175], v[174:175], v[186:187]
	ds_bpermute_b32 v184, v87, v172
	ds_bpermute_b32 v185, v87, v173
	ds_bpermute_b32 v186, v87, v174
	ds_bpermute_b32 v187, v87, v175
	s_waitcnt lgkmcnt(0)
; DI unsigned pk2(float lo, float hi) { f32x2 v = {lo, hi}; bf16x2_t b = __builtin_convertvector(v, bf16x2_t); return __builtin_bit_cast(unsigned, b); }
; DI void normmod_phase(const float* xl, const float* xc, const float* g, const float* modl  , int cshift, int cscale, bf16_t* H, int nrows, int gw, int NGW, int lane,
;                       const float* part  , const float* pgate  , float* xc_out) {
;     ...
;     auto st = [&](const int row, const f32x4 (&v)[4], const float rs) __attribute__((always_inline)) {
;         const float* mp = modl + (size_t)((row < ML) ? (row >> 12) : 16) * 6144;
; #pragma unroll
;         for (int j = 0; j < 4; ++j) { const int c = lane * 4 + 256 * j;
;             const f32x4 gg = *(const f32x4*)(g + c), sh = *(const f32x4*)(mp + cshift * 1024 + c), scl = *(const f32x4*)(mp + cscale * 1024 + c);
;             const f32x4 y = (v[j] * rs) * gg * (scl + 1.f) + sh;
;             u32x2 o; o.x = pk2(y[0], y[1]); o.y = pk2(y[2], y[3]);
;             *(u32x2*)(H + (size_t)row * D + c) = o; } };
;     for (int row = gw * 4; row < (nrows < ML ? nrows : ML); row += NGW * 4) {
;         f32x4 vA[4], vB[4], vC[4], vD[4];
;         float sA = ld(row, vA), sB = ld(row + 1, vB), sC = ld(row + 2, vC), sD = ld(row + 3, vD);
; #pragma unroll
;         for (int o = 1; o < 64; o <<= 1) { sA += __shfl_xor(sA, o); sB += __shfl_xor(sB, o); sC += __shfl_xor(sC, o); sD += __shfl_xor(sD, o); }
;         st(row, vA, rsqrtf(sA * (1.f / D) + EPS)); st(row + 1, vB, rsqrtf(sB * (1.f / D) + EPS));
;         st(row + 2, vC, rsqrtf(sC * (1.f / D) + EPS)); st(row + 3, vD, rsqrtf(sD * (1.f / D) + EPS));
	v_pk_add_f32 v[172:173], v[172:173], v[184:185]
	v_pk_add_f32 v[174:175], v[174:175], v[186:187]
	ds_bpermute_b32 v184, v88, v172
	ds_bpermute_b32 v185, v88, v173
	ds_bpermute_b32 v186, v88, v174
	ds_bpermute_b32 v187, v88, v175
	s_waitcnt lgkmcnt(0)
	v_pk_add_f32 v[172:173], v[172:173], v[184:185]
	v_pk_add_f32 v[174:175], v[174:175], v[186:187]
	v_fma_f32 v172, v172, s34, v178
	v_fma_f32 v173, v173, s34, v178
	v_fma_f32 v174, v174, s34, v178
	v_fma_f32 v175, v175, s34, v178
	v_mul_f32_e32 v184, 0x4b800000, v172
	v_mul_f32_e32 v185, 0x4b800000, v173
	v_mul_f32_e32 v186, 0x4b800000, v174
	v_mul_f32_e32 v187, 0x4b800000, v175
	s_waitcnt vmcnt(8)
	v_cmp_gt_f32_e64 s[50:51], s62, v172
	v_cmp_gt_f32_e64 s[52:53], s62, v173
	v_cmp_gt_f32_e64 s[30:31], s62, v174
	v_cmp_gt_f32_e32 vcc, s62, v175
	s_nop 1
	v_cndmask_b32_e64 v172, v172, v184, s[50:51]
	v_cndmask_b32_e64 v173, v173, v185, s[52:53]
	v_cndmask_b32_e64 v174, v174, v186, s[30:31]
	v_cndmask_b32_e32 v175, v175, v187, vcc
	v_rsq_f32_e32 v172, v172
	v_rsq_f32_e32 v173, v173
	v_rsq_f32_e32 v174, v174
	v_rsq_f32_e32 v175, v175
	s_nop 0
	v_mul_f32_e32 v184, 0x45800000, v172
	v_mul_f32_e32 v185, 0x45800000, v173
	v_mul_f32_e32 v186, 0x45800000, v174
	v_mul_f32_e32 v187, 0x45800000, v175
	v_cndmask_b32_e64 v188, v172, v184, s[50:51]
	v_cndmask_b32_e64 v190, v173, v185, s[52:53]
	v_cndmask_b32_e64 v192, v174, v186, s[30:31]
	v_cndmask_b32_e32 v194, v175, v187, vcc
	v_pk_add_f32 v[126:127], v[126:127], 1.0 op_sel_hi:[1,0]
	v_pk_add_f32 v[128:129], v[128:129], 1.0 op_sel_hi:[1,0]
	v_pk_add_f32 v[130:131], v[130:131], 1.0 op_sel_hi:[1,0]
	v_pk_add_f32 v[132:133], v[132:133], 1.0 op_sel_hi:[1,0]
	v_pk_add_f32 v[134:135], v[134:135], 1.0 op_sel_hi:[1,0]
	v_pk_add_f32 v[136:137], v[136:137], 1.0 op_sel_hi:[1,0]
	v_pk_add_f32 v[138:139], v[138:139], 1.0 op_sel_hi:[1,0]
	v_pk_add_f32 v[140:141], v[140:141], 1.0 op_sel_hi:[1,0]
	v_pk_mul_f32 v[0:1], v[0:1], v[188:189] op_sel_hi:[1,0]
	v_pk_mul_f32 v[2:3], v[2:3], v[188:189] op_sel_hi:[1,0]
	v_pk_mul_f32 v[0:1], v[156:157], v[0:1]
	v_pk_mul_f32 v[2:3], v[158:159], v[2:3]
	v_pk_fma_f32 v[0:1], v[126:127], v[0:1], v[110:111]
	v_pk_fma_f32 v[2:3], v[128:129], v[2:3], v[112:113]
	v_cvt_pk_bf16_f32 v0, v0, v1
	v_cvt_pk_bf16_f32 v1, v2, v3
	global_store_dwordx2 v[198:199], v[0:1], off offset:-3584
	v_pk_mul_f32 v[4:5], v[4:5], v[188:189] op_sel_hi:[1,0]
	v_pk_mul_f32 v[6:7], v[6:7], v[188:189] op_sel_hi:[1,0]
	v_pk_mul_f32 v[4:5], v[160:161], v[4:5]
	v_pk_mul_f32 v[6:7], v[162:163], v[6:7]
	v_pk_fma_f32 v[4:5], v[130:131], v[4:5], v[114:115]
	v_pk_fma_f32 v[6:7], v[132:133], v[6:7], v[116:117]
	v_cvt_pk_bf16_f32 v4, v4, v5
	v_cvt_pk_bf16_f32 v5, v6, v7
	global_store_dwordx2 v[198:199], v[4:5], off offset:-3072
	v_pk_mul_f32 v[8:9], v[8:9], v[188:189] op_sel_hi:[1,0]
	v_pk_mul_f32 v[10:11], v[10:11], v[188:189] op_sel_hi:[1,0]
	v_pk_mul_f32 v[8:9], v[164:165], v[8:9]
	v_pk_mul_f32 v[10:11], v[166:167], v[10:11]
	v_pk_fma_f32 v[8:9], v[134:135], v[8:9], v[118:119]
	v_pk_fma_f32 v[10:11], v[136:137], v[10:11], v[120:121]
	v_cvt_pk_bf16_f32 v8, v8, v9
	v_cvt_pk_bf16_f32 v9, v10, v11
	global_store_dwordx2 v[198:199], v[8:9], off offset:-2560
	v_pk_mul_f32 v[12:13], v[12:13], v[188:189] op_sel_hi:[1,0]
	v_pk_mul_f32 v[14:15], v[14:15], v[188:189] op_sel_hi:[1,0]
	v_pk_mul_f32 v[12:13], v[168:169], v[12:13]
	v_pk_mul_f32 v[14:15], v[170:171], v[14:15]
	v_pk_fma_f32 v[12:13], v[138:139], v[12:13], v[122:123]
	v_pk_fma_f32 v[14:15], v[140:141], v[14:15], v[124:125]
	v_cvt_pk_bf16_f32 v12, v12, v13
	v_cvt_pk_bf16_f32 v13, v14, v15
	global_store_dwordx2 v[198:199], v[12:13], off offset:-2048
	global_load_dwordx4 v[0:3], v76, s[42:43] nt
	global_load_dwordx4 v[4:7], v76, s[42:43] offset:1024 nt
	global_load_dwordx4 v[8:11], v76, s[42:43] offset:2048 nt
	global_load_dwordx4 v[12:15], v76, s[42:43] offset:3072 nt
	v_pk_mul_f32 v[16:17], v[16:17], v[190:191] op_sel_hi:[1,0]
	v_pk_mul_f32 v[18:19], v[18:19], v[190:191] op_sel_hi:[1,0]
	v_pk_mul_f32 v[16:17], v[156:157], v[16:17]
	v_pk_mul_f32 v[18:19], v[158:159], v[18:19]
	v_pk_fma_f32 v[16:17], v[126:127], v[16:17], v[110:111]
	v_pk_fma_f32 v[18:19], v[128:129], v[18:19], v[112:113]
	v_cvt_pk_bf16_f32 v16, v16, v17
	v_cvt_pk_bf16_f32 v17, v18, v19
	global_store_dwordx2 v[198:199], v[16:17], off offset:-1536
	v_pk_mul_f32 v[20:21], v[20:21], v[190:191] op_sel_hi:[1,0]
	v_pk_mul_f32 v[22:23], v[22:23], v[190:191] op_sel_hi:[1,0]
	v_pk_mul_f32 v[20:21], v[160:161], v[20:21]
	v_pk_mul_f32 v[22:23], v[162:163], v[22:23]
	v_pk_fma_f32 v[20:21], v[130:131], v[20:21], v[114:115]
	v_pk_fma_f32 v[22:23], v[132:133], v[22:23], v[116:117]
	v_cvt_pk_bf16_f32 v20, v20, v21
	v_cvt_pk_bf16_f32 v21, v22, v23
	global_store_dwordx2 v[198:199], v[20:21], off offset:-1024
	v_pk_mul_f32 v[24:25], v[24:25], v[190:191] op_sel_hi:[1,0]
	v_pk_mul_f32 v[26:27], v[26:27], v[190:191] op_sel_hi:[1,0]
	v_pk_mul_f32 v[24:25], v[164:165], v[24:25]
	v_pk_mul_f32 v[26:27], v[166:167], v[26:27]
	v_pk_fma_f32 v[24:25], v[134:135], v[24:25], v[118:119]
	v_pk_fma_f32 v[26:27], v[136:137], v[26:27], v[120:121]
	v_cvt_pk_bf16_f32 v24, v24, v25
	v_cvt_pk_bf16_f32 v25, v26, v27
	global_store_dwordx2 v[198:199], v[24:25], off offset:-512
	v_pk_mul_f32 v[28:29], v[28:29], v[190:191] op_sel_hi:[1,0]
	v_pk_mul_f32 v[30:31], v[30:31], v[190:191] op_sel_hi:[1,0]
	v_pk_mul_f32 v[28:29], v[168:169], v[28:29]
	v_pk_mul_f32 v[30:31], v[170:171], v[30:31]
	v_pk_fma_f32 v[28:29], v[138:139], v[28:29], v[122:123]
	v_pk_fma_f32 v[30:31], v[140:141], v[30:31], v[124:125]
	v_cvt_pk_bf16_f32 v28, v28, v29
	v_cvt_pk_bf16_f32 v29, v30, v31
	global_store_dwordx2 v[78:79], v[28:29], off offset:-4096
; DI void normmod_phase(const float* xl, const float* xc, const float* g, const float* modl  , int cshift, int cscale, bf16_t* H, int nrows, int gw, int NGW, int lane,
;                       const float* part  , const float* pgate  , float* xc_out) {
;     auto ld = [&](const int row, f32x4 (&v)[4]) __attribute__((always_inline)) -> float {
;         const bool lat = row < ML;
;         const float* xr = lat ? xl + (size_t)row * D : xc + (size_t)(row - ML) * D;
;         float ss = 0.f;
; #pragma unroll
;         for (int j = 0; j < 4; ++j) { v[j] = *(const f32x4*)(xr + lane * 4 + 256 * j);
;             if (part && !lat) {
;                 const size_t po = (size_t)(row - ML) * D + lane * 4 + 256 * j;
;                 const f32x4 p0 = *(const f32x4*)(part + po), p1 = *(const f32x4*)(part + (size_t)MC * D + po), p2 = *(const f32x4*)(part + (size_t)2 * MC * D + po), p3 = *(const f32x4*)(part + (size_t)3 * MC * D + po);
;                 v[j] = v[j] + *(const f32x4*)(pgate + lane * 4 + 256 * j) * ((p0 + p1) + (p2 + p3));
;                 *(f32x4*)(xc_out + po) = v[j]; }
;             ss += (v[j][0] * v[j][0] + v[j][1] * v[j][1]) + (v[j][2] * v[j][2] + v[j][3] * v[j][3]); }
;         return ss; };
;     auto st = [&](const int row, const f32x4 (&v)[4], const float rs) __attribute__((always_inline)) {
;         const float* mp = modl + (size_t)((row < ML) ? (row >> 12) : 16) * 6144;
; #pragma unroll
;         for (int j = 0; j < 4; ++j) { const int c = lane * 4 + 256 * j;
;             const f32x4 gg = *(const f32x4*)(g + c), sh = *(const f32x4*)(mp + cshift * 1024 + c), scl = *(const f32x4*)(mp + cscale * 1024 + c);
;             const f32x4 y = (v[j] * rs) * gg * (scl + 1.f) + sh;
;             u32x2 o; o.x = pk2(y[0], y[1]); o.y = pk2(y[2], y[3]);
;             *(u32x2*)(H + (size_t)row * D + c) = o; } };
;     for (int row = gw * 4; row < (nrows < ML ? nrows : ML); row += NGW * 4) {
;         f32x4 vA[4], vB[4], vC[4], vD[4];
;         float sA = ld(row, vA), sB = ld(row + 1, vB), sC = ld(row + 2, vC), sD = ld(row + 3, vD);
; #pragma unroll
;         for (int o = 1; o < 64; o <<= 1) { sA += __shfl_xor(sA, o); sB += __shfl_xor(sB, o); sC += __shfl_xor(sC, o); sD += __shfl_xor(sD, o); }
;         st(row, vA, rsqrtf(sA * (1.f / D) + EPS)); st(row + 1, vB, rsqrtf(sB * (1.f / D) + EPS));
	global_load_dwordx4 v[16:19], v76, s[4:5] nt
	global_load_dwordx4 v[20:23], v76, s[4:5] offset:1024 nt
	global_load_dwordx4 v[24:27], v76, s[4:5] offset:2048 nt
	global_load_dwordx4 v[28:31], v76, s[4:5] offset:3072 nt
	v_pk_mul_f32 v[32:33], v[32:33], v[192:193] op_sel_hi:[1,0]
	v_pk_mul_f32 v[34:35], v[34:35], v[192:193] op_sel_hi:[1,0]
	v_pk_mul_f32 v[32:33], v[156:157], v[32:33]
	v_pk_mul_f32 v[34:35], v[158:159], v[34:35]
	v_pk_fma_f32 v[32:33], v[126:127], v[32:33], v[110:111]
	v_pk_fma_f32 v[34:35], v[128:129], v[34:35], v[112:113]
	v_cvt_pk_bf16_f32 v32, v32, v33
	v_cvt_pk_bf16_f32 v33, v34, v35
	global_store_dwordx2 v[78:79], v[32:33], off offset:-3584
	v_pk_mul_f32 v[36:37], v[36:37], v[192:193] op_sel_hi:[1,0]
	v_pk_mul_f32 v[38:39], v[38:39], v[192:193] op_sel_hi:[1,0]
	v_pk_mul_f32 v[36:37], v[160:161], v[36:37]
	v_pk_mul_f32 v[38:39], v[162:163], v[38:39]
	v_pk_fma_f32 v[36:37], v[130:131], v[36:37], v[114:115]
	v_pk_fma_f32 v[38:39], v[132:133], v[38:39], v[116:117]
	v_cvt_pk_bf16_f32 v36, v36, v37
	v_cvt_pk_bf16_f32 v37, v38, v39
	global_store_dwordx2 v[78:79], v[36:37], off offset:-3072
	v_pk_mul_f32 v[40:41], v[40:41], v[192:193] op_sel_hi:[1,0]
	v_pk_mul_f32 v[42:43], v[42:43], v[192:193] op_sel_hi:[1,0]
	v_pk_mul_f32 v[40:41], v[164:165], v[40:41]
	v_pk_mul_f32 v[42:43], v[166:167], v[42:43]
	v_pk_fma_f32 v[40:41], v[134:135], v[40:41], v[118:119]
	v_pk_fma_f32 v[42:43], v[136:137], v[42:43], v[120:121]
	v_cvt_pk_bf16_f32 v40, v40, v41
	v_cvt_pk_bf16_f32 v41, v42, v43
	global_store_dwordx2 v[78:79], v[40:41], off offset:-2560
	v_pk_mul_f32 v[44:45], v[44:45], v[192:193] op_sel_hi:[1,0]
	v_pk_mul_f32 v[46:47], v[46:47], v[192:193] op_sel_hi:[1,0]
	v_pk_mul_f32 v[44:45], v[168:169], v[44:45]
	v_pk_mul_f32 v[46:47], v[170:171], v[46:47]
	v_pk_fma_f32 v[44:45], v[138:139], v[44:45], v[122:123]
	v_pk_fma_f32 v[46:47], v[140:141], v[46:47], v[124:125]
	v_cvt_pk_bf16_f32 v44, v44, v45
	v_cvt_pk_bf16_f32 v45, v46, v47
	global_store_dwordx2 v[78:79], v[44:45], off offset:-2048
	v_pk_mul_f32 v[48:49], v[48:49], v[194:195] op_sel_hi:[1,0]
	v_pk_mul_f32 v[50:51], v[50:51], v[194:195] op_sel_hi:[1,0]
	v_pk_mul_f32 v[48:49], v[156:157], v[48:49]
	v_pk_mul_f32 v[50:51], v[158:159], v[50:51]
	v_pk_fma_f32 v[48:49], v[126:127], v[48:49], v[110:111]
	v_pk_fma_f32 v[50:51], v[128:129], v[50:51], v[112:113]
	v_cvt_pk_bf16_f32 v48, v48, v49
	v_cvt_pk_bf16_f32 v49, v50, v51
	global_store_dwordx2 v[78:79], v[48:49], off offset:-1536
	v_pk_mul_f32 v[52:53], v[52:53], v[194:195] op_sel_hi:[1,0]
	v_pk_mul_f32 v[54:55], v[54:55], v[194:195] op_sel_hi:[1,0]
	v_pk_mul_f32 v[52:53], v[160:161], v[52:53]
	v_pk_mul_f32 v[54:55], v[162:163], v[54:55]
	v_pk_fma_f32 v[52:53], v[130:131], v[52:53], v[114:115]
	v_pk_fma_f32 v[54:55], v[132:133], v[54:55], v[116:117]
	v_cvt_pk_bf16_f32 v52, v52, v53
	v_cvt_pk_bf16_f32 v53, v54, v55
	global_store_dwordx2 v[78:79], v[52:53], off offset:-1024
	v_pk_mul_f32 v[56:57], v[56:57], v[194:195] op_sel_hi:[1,0]
	v_pk_mul_f32 v[58:59], v[58:59], v[194:195] op_sel_hi:[1,0]
	v_pk_mul_f32 v[56:57], v[164:165], v[56:57]
	v_pk_mul_f32 v[58:59], v[166:167], v[58:59]
	v_pk_fma_f32 v[56:57], v[134:135], v[56:57], v[118:119]
	v_pk_fma_f32 v[58:59], v[136:137], v[58:59], v[120:121]
	v_cvt_pk_bf16_f32 v56, v56, v57
	v_cvt_pk_bf16_f32 v57, v58, v59
	global_store_dwordx2 v[78:79], v[56:57], off offset:-512
	v_pk_mul_f32 v[60:61], v[60:61], v[194:195] op_sel_hi:[1,0]
	v_pk_mul_f32 v[62:63], v[62:63], v[194:195] op_sel_hi:[1,0]
	v_pk_mul_f32 v[60:61], v[168:169], v[60:61]
	v_pk_mul_f32 v[62:63], v[170:171], v[62:63]
	v_pk_fma_f32 v[60:61], v[138:139], v[60:61], v[122:123]
	v_pk_fma_f32 v[62:63], v[140:141], v[62:63], v[124:125]
	v_cvt_pk_bf16_f32 v60, v60, v61
	v_cvt_pk_bf16_f32 v61, v62, v63
	global_store_dwordx2 v[78:79], v[60:61], off
	s_add_i32 s20, s20, s26
	v_lshl_add_u64 v[78:79], v[78:79], 0, s[46:47]
	s_add_i32 s4, s20, 0xffff
	s_cmp_gt_i32 s4, 0xffff
	s_cbranch_scc1 .Lnm4_nm1_exit
	s_add_i32 s30, s20, 0xffff
	s_ashr_i32 s30, s30, 12
	s_mul_hi_i32 s31, s30, 0x6000
	s_mulk_i32 s30, 0x6000
	s_add_u32 s50, s16, s30
	s_addc_u32 s51, s17, s31
	s_add_u32 s52, s50, 0x1000
	s_addc_u32 s53, s51, 0
	global_load_dwordx4 v[110:113], v76, s[50:51]
	global_load_dwordx4 v[114:117], v76, s[50:51] offset:1024
	global_load_dwordx4 v[118:121], v76, s[50:51] offset:2048
	global_load_dwordx4 v[122:125], v76, s[50:51] offset:3072
	global_load_dwordx4 v[126:129], v76, s[52:53]
	global_load_dwordx4 v[130:133], v76, s[52:53] offset:1024
	global_load_dwordx4 v[134:137], v76, s[52:53] offset:2048
	global_load_dwordx4 v[138:141], v76, s[52:53] offset:3072
	s_add_i32 s27, s20, s26
	s_add_i32 s27, s27, 0xffff
	s_cmp_gt_i32 s27, 0xffff
	s_cselect_b32 s30, 0, s44
	s_cselect_b32 s31, 0, s45
	s_add_u32 s42, s42, s30
	s_addc_u32 s43, s43, s31
	s_add_u32 s4, s42, 0x1000
	s_addc_u32 s5, s43, 0
	s_add_u32 s24, s42, 0x2000
	s_addc_u32 s25, s43, 0
	s_add_u32 s48, s42, 0x3000
	s_addc_u32 s49, s43, 0
	global_load_dwordx4 v[32:35], v76, s[24:25] nt
	global_load_dwordx4 v[36:39], v76, s[24:25] offset:1024 nt
	global_load_dwordx4 v[40:43], v76, s[24:25] offset:2048 nt
	global_load_dwordx4 v[44:47], v76, s[24:25] offset:3072 nt
	global_load_dwordx4 v[48:51], v76, s[48:49] nt
	global_load_dwordx4 v[52:55], v76, s[48:49] offset:1024 nt
	global_load_dwordx4 v[56:59], v76, s[48:49] offset:2048 nt
	global_load_dwordx4 v[60:63], v76, s[48:49] offset:3072 nt
	s_mov_b32 s30, 0xfffff000
	s_mov_b32 s31, -1
	v_mov_b32_e32 v178, s36
	v_lshl_add_u64 v[198:199], v[78:79], 0, s[30:31]
	s_waitcnt vmcnt(28)
; DI unsigned pk2(float lo, float hi) { f32x2 v = {lo, hi}; bf16x2_t b = __builtin_convertvector(v, bf16x2_t); return __builtin_bit_cast(unsigned, b); }
; DI void normmod_phase(const float* xl, const float* xc, const float* g, const float* modl  , int cshift, int cscale, bf16_t* H, int nrows, int gw, int NGW, int lane,
;                       const float* part  , const float* pgate  , float* xc_out) {
;     auto ld = [&](const int row, f32x4 (&v)[4]) __attribute__((always_inline)) -> float {
;         const bool lat = row < ML;
;         const float* xr = lat ? xl + (size_t)row * D : xc + (size_t)(row - ML) * D;
;         float ss = 0.f;
; #pragma unroll
;         for (int j = 0; j < 4; ++j) { v[j] = *(const f32x4*)(xr + lane * 4 + 256 * j);
;             if (part && !lat) {
;                 const size_t po = (size_t)(row - ML) * D + lane * 4 + 256 * j;
;                 const f32x4 p0 = *(const f32x4*)(part + po), p1 = *(const f32x4*)(part + (size_t)MC * D + po), p2 = *(const f32x4*)(part + (size_t)2 * MC * D + po), p3 = *(const f32x4*)(part + (size_t)3 * MC * D + po);
;                 v[j] = v[j] + *(const f32x4*)(pgate + lane * 4 + 256 * j) * ((p0 + p1) + (p2 + p3));
;                 *(f32x4*)(xc_out + po) = v[j]; }
;             ss += (v[j][0] * v[j][0] + v[j][1] * v[j][1]) + (v[j][2] * v[j][2] + v[j][3] * v[j][3]); }
;         return ss; };
;     auto st = [&](const int row, const f32x4 (&v)[4], const float rs) __attribute__((always_inline)) {
;         const float* mp = modl + (size_t)((row < ML) ? (row >> 12) : 16) * 6144;
; #pragma unroll
;         for (int j = 0; j < 4; ++j) { const int c = lane * 4 + 256 * j;
;             const f32x4 gg = *(const f32x4*)(g + c), sh = *(const f32x4*)(mp + cshift * 1024 + c), scl = *(const f32x4*)(mp + cscale * 1024 + c);
;             const f32x4 y = (v[j] * rs) * gg * (scl + 1.f) + sh;
;             u32x2 o; o.x = pk2(y[0], y[1]); o.y = pk2(y[2], y[3]);
;             *(u32x2*)(H + (size_t)row * D + c) = o; } };
;     for (int row = gw * 4; row < (nrows < ML ? nrows : ML); row += NGW * 4) {
;         f32x4 vA[4], vB[4], vC[4], vD[4];
;         float sA = ld(row, vA), sB = ld(row + 1, vB), sC = ld(row + 2, vC), sD = ld(row + 3, vD);
; #pragma unroll
;         for (int o = 1; o < 64; o <<= 1) { sA += __shfl_xor(sA, o); sB += __shfl_xor(sB, o); sC += __shfl_xor(sC, o); sD += __shfl_xor(sD, o); }
	v_mul_f32_e32 v176, v1, v1
	v_mul_f32_e32 v177, v3, v3
	v_fmac_f32_e32 v176, v0, v0
	v_fmac_f32_e32 v177, v2, v2
	v_add_f32_e32 v172, v176, v177
	v_mul_f32_e32 v176, v5, v5
	v_mul_f32_e32 v177, v7, v7
	v_fmac_f32_e32 v176, v4, v4
	v_fmac_f32_e32 v177, v6, v6
	v_add_f32_e32 v176, v176, v177
	v_add_f32_e32 v172, v172, v176
	v_mul_f32_e32 v176, v9, v9
	v_mul_f32_e32 v177, v11, v11
	v_fmac_f32_e32 v176, v8, v8
	v_fmac_f32_e32 v177, v10, v10
	v_add_f32_e32 v176, v176, v177
	v_add_f32_e32 v172, v172, v176
	v_mul_f32_e32 v176, v13, v13
	v_mul_f32_e32 v177, v15, v15
	v_fmac_f32_e32 v176, v12, v12
	v_fmac_f32_e32 v177, v14, v14
	v_add_f32_e32 v176, v176, v177
	v_add_f32_e32 v172, v172, v176
	s_waitcnt vmcnt(24)
	v_mul_f32_e32 v176, v17, v17
	v_mul_f32_e32 v177, v19, v19
	v_fmac_f32_e32 v176, v16, v16
	v_fmac_f32_e32 v177, v18, v18
	v_add_f32_e32 v173, v176, v177
	v_mul_f32_e32 v176, v21, v21
	v_mul_f32_e32 v177, v23, v23
	v_fmac_f32_e32 v176, v20, v20
	v_fmac_f32_e32 v177, v22, v22
	v_add_f32_e32 v176, v176, v177
	v_add_f32_e32 v173, v173, v176
	v_mul_f32_e32 v176, v25, v25
	v_mul_f32_e32 v177, v27, v27
	v_fmac_f32_e32 v176, v24, v24
	v_fmac_f32_e32 v177, v26, v26
	v_add_f32_e32 v176, v176, v177
	v_add_f32_e32 v173, v173, v176
	v_mul_f32_e32 v176, v29, v29
	v_mul_f32_e32 v177, v31, v31
	v_fmac_f32_e32 v176, v28, v28
	v_fmac_f32_e32 v177, v30, v30
	v_add_f32_e32 v176, v176, v177
	v_add_f32_e32 v173, v173, v176
	s_waitcnt vmcnt(16)
	v_mul_f32_e32 v176, v215, v215
	v_mul_f32_e32 v177, v217, v217
	v_fmac_f32_e32 v176, v214, v214
	v_fmac_f32_e32 v177, v216, v216
	v_add_f32_e32 v174, v176, v177
	v_mul_f32_e32 v176, v219, v219
	v_mul_f32_e32 v177, v221, v221
	v_fmac_f32_e32 v176, v218, v218
	v_fmac_f32_e32 v177, v220, v220
	v_add_f32_e32 v176, v176, v177
	v_add_f32_e32 v174, v174, v176
	v_mul_f32_e32 v176, v223, v223
	v_mul_f32_e32 v177, v225, v225
	v_fmac_f32_e32 v176, v222, v222
	v_fmac_f32_e32 v177, v224, v224
	v_add_f32_e32 v176, v176, v177
	v_add_f32_e32 v174, v174, v176
	v_mul_f32_e32 v176, v227, v227
	v_mul_f32_e32 v177, v229, v229
	v_fmac_f32_e32 v176, v226, v226
	v_fmac_f32_e32 v177, v228, v228
	v_add_f32_e32 v176, v176, v177
	v_add_f32_e32 v174, v174, v176
	v_mul_f32_e32 v176, v231, v231
	v_mul_f32_e32 v177, v233, v233
	v_fmac_f32_e32 v176, v230, v230
	v_fmac_f32_e32 v177, v232, v232
	v_add_f32_e32 v175, v176, v177
	v_mul_f32_e32 v176, v235, v235
	v_mul_f32_e32 v177, v237, v237
	v_fmac_f32_e32 v176, v234, v234
	v_fmac_f32_e32 v177, v236, v236
	v_add_f32_e32 v176, v176, v177
	v_add_f32_e32 v175, v175, v176
	v_mul_f32_e32 v176, v239, v239
	v_mul_f32_e32 v177, v241, v241
	v_fmac_f32_e32 v176, v238, v238
	v_fmac_f32_e32 v177, v240, v240
	v_add_f32_e32 v176, v176, v177
	v_add_f32_e32 v175, v175, v176
	v_mul_f32_e32 v176, v243, v243
	v_mul_f32_e32 v177, v245, v245
	v_fmac_f32_e32 v176, v242, v242
	v_fmac_f32_e32 v177, v244, v244
	v_add_f32_e32 v176, v176, v177
	v_add_f32_e32 v175, v175, v176
	ds_bpermute_b32 v184, v83, v172
	ds_bpermute_b32 v185, v83, v173
	ds_bpermute_b32 v186, v83, v174
	ds_bpermute_b32 v187, v83, v175
	s_waitcnt lgkmcnt(0)
	v_pk_add_f32 v[172:173], v[172:173], v[184:185]
	v_pk_add_f32 v[174:175], v[174:175], v[186:187]
	ds_bpermute_b32 v184, v84, v172
	ds_bpermute_b32 v185, v84, v173
	ds_bpermute_b32 v186, v84, v174
	ds_bpermute_b32 v187, v84, v175
	s_waitcnt lgkmcnt(0)
	v_pk_add_f32 v[172:173], v[172:173], v[184:185]
	v_pk_add_f32 v[174:175], v[174:175], v[186:187]
	ds_bpermute_b32 v184, v85, v172
	ds_bpermute_b32 v185, v85, v173
	ds_bpermute_b32 v186, v85, v174
	ds_bpermute_b32 v187, v85, v175
	s_waitcnt lgkmcnt(0)
	v_pk_add_f32 v[172:173], v[172:173], v[184:185]
	v_pk_add_f32 v[174:175], v[174:175], v[186:187]
	ds_bpermute_b32 v184, v86, v172
	ds_bpermute_b32 v185, v86, v173
	ds_bpermute_b32 v186, v86, v174
	ds_bpermute_b32 v187, v86, v175
	s_waitcnt lgkmcnt(0)
	v_pk_add_f32 v[172:173], v[172:173], v[184:185]
	v_pk_add_f32 v[174:175], v[174:175], v[186:187]
	ds_bpermute_b32 v184, v87, v172
	ds_bpermute_b32 v185, v87, v173
	ds_bpermute_b32 v186, v87, v174
	ds_bpermute_b32 v187, v87, v175
	s_waitcnt lgkmcnt(0)
	v_pk_add_f32 v[172:173], v[172:173], v[184:185]
	v_pk_add_f32 v[174:175], v[174:175], v[186:187]
	ds_bpermute_b32 v184, v88, v172
	ds_bpermute_b32 v185, v88, v173
	ds_bpermute_b32 v186, v88, v174
	ds_bpermute_b32 v187, v88, v175
	s_waitcnt lgkmcnt(0)
	v_pk_add_f32 v[172:173], v[172:173], v[184:185]
	v_pk_add_f32 v[174:175], v[174:175], v[186:187]
	v_fma_f32 v172, v172, s34, v178
	v_fma_f32 v173, v173, s34, v178
	v_fma_f32 v174, v174, s34, v178
	v_fma_f32 v175, v175, s34, v178
	v_mul_f32_e32 v184, 0x4b800000, v172
	v_mul_f32_e32 v185, 0x4b800000, v173
	v_mul_f32_e32 v186, 0x4b800000, v174
	v_mul_f32_e32 v187, 0x4b800000, v175
	s_waitcnt vmcnt(8)
; DI unsigned pk2(float lo, float hi) { f32x2 v = {lo, hi}; bf16x2_t b = __builtin_convertvector(v, bf16x2_t); return __builtin_bit_cast(unsigned, b); }
; DI void normmod_phase(const float* xl, const float* xc, const float* g, const float* modl  , int cshift, int cscale, bf16_t* H, int nrows, int gw, int NGW, int lane,
;                       const float* part  , const float* pgate  , float* xc_out) {
;     ...
;     auto st = [&](const int row, const f32x4 (&v)[4], const float rs) __attribute__((always_inline)) {
;         const float* mp = modl + (size_t)((row < ML) ? (row >> 12) : 16) * 6144;
; #pragma unroll
;         for (int j = 0; j < 4; ++j) { const int c = lane * 4 + 256 * j;
;             const f32x4 gg = *(const f32x4*)(g + c), sh = *(const f32x4*)(mp + cshift * 1024 + c), scl = *(const f32x4*)(mp + cscale * 1024 + c);
;             const f32x4 y = (v[j] * rs) * gg * (scl + 1.f) + sh;
;             u32x2 o; o.x = pk2(y[0], y[1]); o.y = pk2(y[2], y[3]);
;             *(u32x2*)(H + (size_t)row * D + c) = o; } };
;     for (int row = gw * 4; row < (nrows < ML ? nrows : ML); row += NGW * 4) {
;         f32x4 vA[4], vB[4], vC[4], vD[4];
;         float sA = ld(row, vA), sB = ld(row + 1, vB), sC = ld(row + 2, vC), sD = ld(row + 3, vD);
; #pragma unroll
;         for (int o = 1; o < 64; o <<= 1) { sA += __shfl_xor(sA, o); sB += __shfl_xor(sB, o); sC += __shfl_xor(sC, o); sD += __shfl_xor(sD, o); }
;         st(row, vA, rsqrtf(sA * (1.f / D) + EPS)); st(row + 1, vB, rsqrtf(sB * (1.f / D) + EPS));
;         st(row + 2, vC, rsqrtf(sC * (1.f / D) + EPS)); st(row + 3, vD, rsqrtf(sD * (1.f / D) + EPS));
	v_cmp_gt_f32_e64 s[50:51], s62, v172
	v_cmp_gt_f32_e64 s[52:53], s62, v173
	v_cmp_gt_f32_e64 s[30:31], s62, v174
	v_cmp_gt_f32_e32 vcc, s62, v175
	s_nop 1
	v_cndmask_b32_e64 v172, v172, v184, s[50:51]
	v_cndmask_b32_e64 v173, v173, v185, s[52:53]
	v_cndmask_b32_e64 v174, v174, v186, s[30:31]
	v_cndmask_b32_e32 v175, v175, v187, vcc
	v_rsq_f32_e32 v172, v172
	v_rsq_f32_e32 v173, v173
	v_rsq_f32_e32 v174, v174
	v_rsq_f32_e32 v175, v175
	s_nop 0
	v_mul_f32_e32 v184, 0x45800000, v172
	v_mul_f32_e32 v185, 0x45800000, v173
	v_mul_f32_e32 v186, 0x45800000, v174
	v_mul_f32_e32 v187, 0x45800000, v175
	v_cndmask_b32_e64 v188, v172, v184, s[50:51]
	v_cndmask_b32_e64 v190, v173, v185, s[52:53]
	v_cndmask_b32_e64 v192, v174, v186, s[30:31]
	v_cndmask_b32_e32 v194, v175, v187, vcc
	v_pk_add_f32 v[126:127], v[126:127], 1.0 op_sel_hi:[1,0]
	v_pk_add_f32 v[128:129], v[128:129], 1.0 op_sel_hi:[1,0]
	v_pk_add_f32 v[130:131], v[130:131], 1.0 op_sel_hi:[1,0]
	v_pk_add_f32 v[132:133], v[132:133], 1.0 op_sel_hi:[1,0]
	v_pk_add_f32 v[134:135], v[134:135], 1.0 op_sel_hi:[1,0]
	v_pk_add_f32 v[136:137], v[136:137], 1.0 op_sel_hi:[1,0]
	v_pk_add_f32 v[138:139], v[138:139], 1.0 op_sel_hi:[1,0]
	v_pk_add_f32 v[140:141], v[140:141], 1.0 op_sel_hi:[1,0]
	v_pk_mul_f32 v[0:1], v[0:1], v[188:189] op_sel_hi:[1,0]
	v_pk_mul_f32 v[2:3], v[2:3], v[188:189] op_sel_hi:[1,0]
	v_pk_mul_f32 v[0:1], v[156:157], v[0:1]
	v_pk_mul_f32 v[2:3], v[158:159], v[2:3]
	v_pk_fma_f32 v[0:1], v[126:127], v[0:1], v[110:111]
	v_pk_fma_f32 v[2:3], v[128:129], v[2:3], v[112:113]
	v_cvt_pk_bf16_f32 v0, v0, v1
	v_cvt_pk_bf16_f32 v1, v2, v3
	global_store_dwordx2 v[198:199], v[0:1], off offset:-3584
	v_pk_mul_f32 v[4:5], v[4:5], v[188:189] op_sel_hi:[1,0]
	v_pk_mul_f32 v[6:7], v[6:7], v[188:189] op_sel_hi:[1,0]
	v_pk_mul_f32 v[4:5], v[160:161], v[4:5]
	v_pk_mul_f32 v[6:7], v[162:163], v[6:7]
	v_pk_fma_f32 v[4:5], v[130:131], v[4:5], v[114:115]
	v_pk_fma_f32 v[6:7], v[132:133], v[6:7], v[116:117]
	v_cvt_pk_bf16_f32 v4, v4, v5
	v_cvt_pk_bf16_f32 v5, v6, v7
	global_store_dwordx2 v[198:199], v[4:5], off offset:-3072
	v_pk_mul_f32 v[8:9], v[8:9], v[188:189] op_sel_hi:[1,0]
	v_pk_mul_f32 v[10:11], v[10:11], v[188:189] op_sel_hi:[1,0]
	v_pk_mul_f32 v[8:9], v[164:165], v[8:9]
	v_pk_mul_f32 v[10:11], v[166:167], v[10:11]
	v_pk_fma_f32 v[8:9], v[134:135], v[8:9], v[118:119]
	v_pk_fma_f32 v[10:11], v[136:137], v[10:11], v[120:121]
	v_cvt_pk_bf16_f32 v8, v8, v9
	v_cvt_pk_bf16_f32 v9, v10, v11
	global_store_dwordx2 v[198:199], v[8:9], off offset:-2560
	v_pk_mul_f32 v[12:13], v[12:13], v[188:189] op_sel_hi:[1,0]
	v_pk_mul_f32 v[14:15], v[14:15], v[188:189] op_sel_hi:[1,0]
	v_pk_mul_f32 v[12:13], v[168:169], v[12:13]
	v_pk_mul_f32 v[14:15], v[170:171], v[14:15]
	v_pk_fma_f32 v[12:13], v[138:139], v[12:13], v[122:123]
	v_pk_fma_f32 v[14:15], v[140:141], v[14:15], v[124:125]
	v_cvt_pk_bf16_f32 v12, v12, v13
	v_cvt_pk_bf16_f32 v13, v14, v15
	global_store_dwordx2 v[198:199], v[12:13], off offset:-2048
	global_load_dwordx4 v[0:3], v76, s[42:43] nt
	global_load_dwordx4 v[4:7], v76, s[42:43] offset:1024 nt
	global_load_dwordx4 v[8:11], v76, s[42:43] offset:2048 nt
	global_load_dwordx4 v[12:15], v76, s[42:43] offset:3072 nt
	v_pk_mul_f32 v[16:17], v[16:17], v[190:191] op_sel_hi:[1,0]
	v_pk_mul_f32 v[18:19], v[18:19], v[190:191] op_sel_hi:[1,0]
	v_pk_mul_f32 v[16:17], v[156:157], v[16:17]
	v_pk_mul_f32 v[18:19], v[158:159], v[18:19]
	v_pk_fma_f32 v[16:17], v[126:127], v[16:17], v[110:111]
	v_pk_fma_f32 v[18:19], v[128:129], v[18:19], v[112:113]
	v_cvt_pk_bf16_f32 v16, v16, v17
	v_cvt_pk_bf16_f32 v17, v18, v19
	global_store_dwordx2 v[198:199], v[16:17], off offset:-1536
	v_pk_mul_f32 v[20:21], v[20:21], v[190:191] op_sel_hi:[1,0]
	v_pk_mul_f32 v[22:23], v[22:23], v[190:191] op_sel_hi:[1,0]
	v_pk_mul_f32 v[20:21], v[160:161], v[20:21]
	v_pk_mul_f32 v[22:23], v[162:163], v[22:23]
	v_pk_fma_f32 v[20:21], v[130:131], v[20:21], v[114:115]
	v_pk_fma_f32 v[22:23], v[132:133], v[22:23], v[116:117]
	v_cvt_pk_bf16_f32 v20, v20, v21
	v_cvt_pk_bf16_f32 v21, v22, v23
	global_store_dwordx2 v[198:199], v[20:21], off offset:-1024
	v_pk_mul_f32 v[24:25], v[24:25], v[190:191] op_sel_hi:[1,0]
	v_pk_mul_f32 v[26:27], v[26:27], v[190:191] op_sel_hi:[1,0]
	v_pk_mul_f32 v[24:25], v[164:165], v[24:25]
	v_pk_mul_f32 v[26:27], v[166:167], v[26:27]
	v_pk_fma_f32 v[24:25], v[134:135], v[24:25], v[118:119]
	v_pk_fma_f32 v[26:27], v[136:137], v[26:27], v[120:121]
	v_cvt_pk_bf16_f32 v24, v24, v25
	v_cvt_pk_bf16_f32 v25, v26, v27
	global_store_dwordx2 v[198:199], v[24:25], off offset:-512
	v_pk_mul_f32 v[28:29], v[28:29], v[190:191] op_sel_hi:[1,0]
	v_pk_mul_f32 v[30:31], v[30:31], v[190:191] op_sel_hi:[1,0]
	v_pk_mul_f32 v[28:29], v[168:169], v[28:29]
	v_pk_mul_f32 v[30:31], v[170:171], v[30:31]
	v_pk_fma_f32 v[28:29], v[138:139], v[28:29], v[122:123]
	v_pk_fma_f32 v[30:31], v[140:141], v[30:31], v[124:125]
	v_cvt_pk_bf16_f32 v28, v28, v29
	v_cvt_pk_bf16_f32 v29, v30, v31
	global_store_dwordx2 v[78:79], v[28:29], off offset:-4096
	global_load_dwordx4 v[16:19], v76, s[4:5] nt
	global_load_dwordx4 v[20:23], v76, s[4:5] offset:1024 nt
	global_load_dwordx4 v[24:27], v76, s[4:5] offset:2048 nt
	global_load_dwordx4 v[28:31], v76, s[4:5] offset:3072 nt
	v_pk_mul_f32 v[214:215], v[214:215], v[192:193] op_sel_hi:[1,0]
	v_pk_mul_f32 v[216:217], v[216:217], v[192:193] op_sel_hi:[1,0]
; DI unsigned pk2(float lo, float hi) { f32x2 v = {lo, hi}; bf16x2_t b = __builtin_convertvector(v, bf16x2_t); return __builtin_bit_cast(unsigned, b); }
; DI void normmod_phase(const float* xl, const float* xc, const float* g, const float* modl  , int cshift, int cscale, bf16_t* H, int nrows, int gw, int NGW, int lane,
;                       const float* part  , const float* pgate  , float* xc_out) {
;     ...
;     auto st = [&](const int row, const f32x4 (&v)[4], const float rs) __attribute__((always_inline)) {
;         const float* mp = modl + (size_t)((row < ML) ? (row >> 12) : 16) * 6144;
; #pragma unroll
;         for (int j = 0; j < 4; ++j) { const int c = lane * 4 + 256 * j;
;             const f32x4 gg = *(const f32x4*)(g + c), sh = *(const f32x4*)(mp + cshift * 1024 + c), scl = *(const f32x4*)(mp + cscale * 1024 + c);
;             const f32x4 y = (v[j] * rs) * gg * (scl + 1.f) + sh;
;             u32x2 o; o.x = pk2(y[0], y[1]); o.y = pk2(y[2], y[3]);
;             *(u32x2*)(H + (size_t)row * D + c) = o; } };
;     for (int row = gw * 4; row < (nrows < ML ? nrows : ML); row += NGW * 4) {
;         f32x4 vA[4], vB[4], vC[4], vD[4];
;         float sA = ld(row, vA), sB = ld(row + 1, vB), sC = ld(row + 2, vC), sD = ld(row + 3, vD);
; #pragma unroll
;         for (int o = 1; o < 64; o <<= 1) { sA += __shfl_xor(sA, o); sB += __shfl_xor(sB, o); sC += __shfl_xor(sC, o); sD += __shfl_xor(sD, o); }
;         st(row, vA, rsqrtf(sA * (1.f / D) + EPS)); st(row + 1, vB, rsqrtf(sB * (1.f / D) + EPS));
;         st(row + 2, vC, rsqrtf(sC * (1.f / D) + EPS)); st(row + 3, vD, rsqrtf(sD * (1.f / D) + EPS));
;     }
;     for (int row = ML + gw * 2; row < nrows; row += NGW * 2) {
	v_pk_mul_f32 v[214:215], v[156:157], v[214:215]
	v_pk_mul_f32 v[216:217], v[158:159], v[216:217]
	v_pk_fma_f32 v[214:215], v[126:127], v[214:215], v[110:111]
	v_pk_fma_f32 v[216:217], v[128:129], v[216:217], v[112:113]
	v_cvt_pk_bf16_f32 v214, v214, v215
	v_cvt_pk_bf16_f32 v215, v216, v217
	global_store_dwordx2 v[78:79], v[214:215], off offset:-3584
	v_pk_mul_f32 v[218:219], v[218:219], v[192:193] op_sel_hi:[1,0]
	v_pk_mul_f32 v[220:221], v[220:221], v[192:193] op_sel_hi:[1,0]
	v_pk_mul_f32 v[218:219], v[160:161], v[218:219]
	v_pk_mul_f32 v[220:221], v[162:163], v[220:221]
	v_pk_fma_f32 v[218:219], v[130:131], v[218:219], v[114:115]
	v_pk_fma_f32 v[220:221], v[132:133], v[220:221], v[116:117]
	v_cvt_pk_bf16_f32 v218, v218, v219
	v_cvt_pk_bf16_f32 v219, v220, v221
	global_store_dwordx2 v[78:79], v[218:219], off offset:-3072
	v_pk_mul_f32 v[222:223], v[222:223], v[192:193] op_sel_hi:[1,0]
	v_pk_mul_f32 v[224:225], v[224:225], v[192:193] op_sel_hi:[1,0]
	v_pk_mul_f32 v[222:223], v[164:165], v[222:223]
	v_pk_mul_f32 v[224:225], v[166:167], v[224:225]
	v_pk_fma_f32 v[222:223], v[134:135], v[222:223], v[118:119]
	v_pk_fma_f32 v[224:225], v[136:137], v[224:225], v[120:121]
	v_cvt_pk_bf16_f32 v222, v222, v223
	v_cvt_pk_bf16_f32 v223, v224, v225
	global_store_dwordx2 v[78:79], v[222:223], off offset:-2560
	v_pk_mul_f32 v[226:227], v[226:227], v[192:193] op_sel_hi:[1,0]
	v_pk_mul_f32 v[228:229], v[228:229], v[192:193] op_sel_hi:[1,0]
	v_pk_mul_f32 v[226:227], v[168:169], v[226:227]
	v_pk_mul_f32 v[228:229], v[170:171], v[228:229]
	v_pk_fma_f32 v[226:227], v[138:139], v[226:227], v[122:123]
	v_pk_fma_f32 v[228:229], v[140:141], v[228:229], v[124:125]
	v_cvt_pk_bf16_f32 v226, v226, v227
	v_cvt_pk_bf16_f32 v227, v228, v229
	global_store_dwordx2 v[78:79], v[226:227], off offset:-2048
	v_pk_mul_f32 v[230:231], v[230:231], v[194:195] op_sel_hi:[1,0]
	v_pk_mul_f32 v[232:233], v[232:233], v[194:195] op_sel_hi:[1,0]
	v_pk_mul_f32 v[230:231], v[156:157], v[230:231]
	v_pk_mul_f32 v[232:233], v[158:159], v[232:233]
	v_pk_fma_f32 v[230:231], v[126:127], v[230:231], v[110:111]
	v_pk_fma_f32 v[232:233], v[128:129], v[232:233], v[112:113]
	v_cvt_pk_bf16_f32 v230, v230, v231
	v_cvt_pk_bf16_f32 v231, v232, v233
	global_store_dwordx2 v[78:79], v[230:231], off offset:-1536
	v_pk_mul_f32 v[234:235], v[234:235], v[194:195] op_sel_hi:[1,0]
	v_pk_mul_f32 v[236:237], v[236:237], v[194:195] op_sel_hi:[1,0]
	v_pk_mul_f32 v[234:235], v[160:161], v[234:235]
	v_pk_mul_f32 v[236:237], v[162:163], v[236:237]
	v_pk_fma_f32 v[234:235], v[130:131], v[234:235], v[114:115]
	v_pk_fma_f32 v[236:237], v[132:133], v[236:237], v[116:117]
	v_cvt_pk_bf16_f32 v234, v234, v235
	v_cvt_pk_bf16_f32 v235, v236, v237
	global_store_dwordx2 v[78:79], v[234:235], off offset:-1024
	v_pk_mul_f32 v[238:239], v[238:239], v[194:195] op_sel_hi:[1,0]
	v_pk_mul_f32 v[240:241], v[240:241], v[194:195] op_sel_hi:[1,0]
	v_pk_mul_f32 v[238:239], v[164:165], v[238:239]
	v_pk_mul_f32 v[240:241], v[166:167], v[240:241]
	v_pk_fma_f32 v[238:239], v[134:135], v[238:239], v[118:119]
	v_pk_fma_f32 v[240:241], v[136:137], v[240:241], v[120:121]
	v_cvt_pk_bf16_f32 v238, v238, v239
	v_cvt_pk_bf16_f32 v239, v240, v241
	global_store_dwordx2 v[78:79], v[238:239], off offset:-512
	v_pk_mul_f32 v[242:243], v[242:243], v[194:195] op_sel_hi:[1,0]
	v_pk_mul_f32 v[244:245], v[244:245], v[194:195] op_sel_hi:[1,0]
	v_pk_mul_f32 v[242:243], v[168:169], v[242:243]
	v_pk_mul_f32 v[244:245], v[170:171], v[244:245]
	v_pk_fma_f32 v[242:243], v[138:139], v[242:243], v[122:123]
	v_pk_fma_f32 v[244:245], v[140:141], v[244:245], v[124:125]
	v_cvt_pk_bf16_f32 v242, v242, v243
	v_cvt_pk_bf16_f32 v243, v244, v245
	global_store_dwordx2 v[78:79], v[242:243], off
	s_add_i32 s20, s20, s26
	v_lshl_add_u64 v[78:79], v[78:79], 0, s[46:47]
	s_add_i32 s4, s20, 0xffff
	s_cmp_gt_i32 s4, 0xffff
	s_cbranch_scc0 .LBB0_557
.Lnm4_nm1_exit:
	s_waitcnt vmcnt(0)
.LBB0_593:
	s_cmpk_gt_i32 s56, 0x7ff
	s_cbranch_scc1 .LBB0_620
	s_waitcnt vmcnt(5)
	v_xor_b32_e32 v0, 1, v210
	v_cmp_lt_i32_e32 vcc, v0, v250
	s_lshl_b32 s20, s56, 1
	s_add_i32 s4, s20, 0x10000
	v_cndmask_b32_e32 v0, v210, v0, vcc
	v_lshlrev_b32_e32 v34, 2, v0
	v_xor_b32_e32 v0, 2, v210
	v_cmp_lt_i32_e32 vcc, v0, v250
	s_ashr_i32 s5, s4, 31
	s_lshl_b32 s26, s33, 4
	v_cndmask_b32_e32 v0, v210, v0, vcc
	v_cmp_lt_i32_e32 vcc, v251, v250
	v_lshlrev_b32_e32 v35, 2, v0
	s_lshl_b64 s[24:25], s[4:5], 12
	v_cndmask_b32_e32 v0, v210, v251, vcc
	v_lshlrev_b32_e32 v36, 2, v0
	v_xor_b32_e32 v0, 8, v210
	s_add_u32 s42, s10, s24
	v_cmp_lt_i32_e32 vcc, v0, v250
	s_addc_u32 s43, s11, s25
	s_ashr_i32 s27, s26, 31
	v_cndmask_b32_e32 v0, v210, v0, vcc
	s_lshl_b64 s[44:45], s[26:27], 12
	s_lshl_b64 s[4:5], s[4:5], 11
	v_lshlrev_b32_e32 v37, 2, v0
	v_xor_b32_e32 v0, 16, v210
	s_add_u32 s4, s23, s4
	v_cmp_lt_i32_e32 vcc, v0, v250
	s_addc_u32 s5, 0, s5
	v_readlane_b32 s12, v254, 28
	v_cndmask_b32_e32 v0, v210, v0, vcc
	s_add_u32 s23, s12, s78
	v_readlane_b32 s12, v254, 29
	v_lshlrev_b32_e32 v38, 2, v0
	v_xor_b32_e32 v0, 32, v210
	s_addc_u32 s24, s12, s79
	v_cmp_lt_i32_e32 vcc, v0, v250
	s_add_u32 s4, s23, s4
	v_mov_b32_e32 v75, v149
	v_cndmask_b32_e32 v0, v210, v0, vcc
	s_addc_u32 s5, s24, s5
	v_lshlrev_b32_e32 v39, 2, v0
	v_lshl_add_u64 v[32:33], s[4:5], 0, v[74:75]
	s_lshl_b64 s[46:47], s[26:27], 11
	s_branch .LBB0_596
